# hand-written SwiGLU GEMM epilogue (packed along columns, no operand shuffles, interleaved chains); bit-identical math
# speedup vs baseline: 1.0170x; 1.0170x over previous
.LBB0_312:
	s_lshl_b32 s12, s72, 12
	s_and_b32 s12, s12, 0x1000
	s_add_i32 s12, s12, 0x20000
	v_lshl_add_u32 v194, s7, 8, v1
	s_lshl_b32 s7, s68, 2
	s_add_i32 s7, s12, s7
	v_lshl_add_u32 v54, v163, 2, s7
	v_add_u32_e32 v189, s12, v186
	ds_read_b128 v[146:149], v54 offset:2048
	ds_read_b128 v[150:153], v54 offset:2064
	ds_read_b128 v[174:177], v54 offset:2560
	ds_read_b128 v[178:181], v54 offset:2576
	ds_read_b128 v[182:185], v54 offset:3072
	ds_read_b128 v[66:69], v54 offset:3088
	ds_read_b128 v[70:73], v54 offset:3584
	ds_read_b128 v[50:53], v54 offset:3600
	ds_read_b64 v[56:57], v189
	v_mov_b64_e32 v[190:191], s[10:11]
	v_lshl_or_b32 v195, s6, 7, v187
	s_mov_b32 s12, 0xbfb8aa3b
	v_mad_i64_i32 v[190:191], vcc, v194, s83, v[190:191]
	v_lshlrev_b32_e32 v195, 1, v195
	ds_read_b64 v[192:193], v189 offset:128
	v_add_co_u32_e32 v190, vcc, v190, v195
	s_nop 1
	v_addc_co_u32_e32 v191, vcc, 0, v191, vcc
	s_waitcnt lgkmcnt(1)
	v_pk_fma_f32 v[142:143], v[146:147], v[56:57], v[142:143] op_sel_hi:[1,0,1] neg_lo:[1,0,0] neg_hi:[1,0,0]
	v_pk_fma_f32 v[144:145], v[148:149], v[56:57], v[144:145] op_sel_hi:[1,0,1] neg_lo:[1,0,0] neg_hi:[1,0,0]
	v_pk_fma_f32 v[134:135], v[150:151], v[56:57], v[134:135] op_sel_hi:[1,0,1] neg_lo:[1,0,0] neg_hi:[1,0,0]
	v_pk_fma_f32 v[136:137], v[152:153], v[56:57], v[136:137] op_sel_hi:[1,0,1] neg_lo:[1,0,0] neg_hi:[1,0,0]
	v_pk_fma_f32 v[138:139], v[174:175], v[56:57], v[138:139] op_sel_hi:[1,0,1] neg_lo:[1,0,0] neg_hi:[1,0,0]
	v_pk_fma_f32 v[140:141], v[176:177], v[56:57], v[140:141] op_sel_hi:[1,0,1] neg_lo:[1,0,0] neg_hi:[1,0,0]
	v_pk_fma_f32 v[130:131], v[178:179], v[56:57], v[130:131] op_sel_hi:[1,0,1] neg_lo:[1,0,0] neg_hi:[1,0,0]
	v_pk_fma_f32 v[132:133], v[180:181], v[56:57], v[132:133] op_sel_hi:[1,0,1] neg_lo:[1,0,0] neg_hi:[1,0,0]
	v_pk_fma_f32 v[142:143], v[56:57], v[142:143], v[182:183] op_sel:[1,0,0]
	v_pk_fma_f32 v[144:145], v[56:57], v[144:145], v[184:185] op_sel:[1,0,0]
	v_pk_fma_f32 v[134:135], v[56:57], v[134:135], v[66:67] op_sel:[1,0,0]
	v_pk_fma_f32 v[136:137], v[56:57], v[136:137], v[68:69] op_sel:[1,0,0]
	v_pk_fma_f32 v[138:139], v[56:57], v[138:139], v[70:71] op_sel:[1,0,0]
	v_pk_fma_f32 v[140:141], v[56:57], v[140:141], v[72:73] op_sel:[1,0,0]
	v_pk_fma_f32 v[130:131], v[56:57], v[130:131], v[50:51] op_sel:[1,0,0]
	v_pk_fma_f32 v[132:133], v[56:57], v[132:133], v[52:53] op_sel:[1,0,0]
	ds_read_b64 v[56:57], v189 offset:256
	v_pk_mul_f32 v[194:195], v[142:143], s[12:13] op_sel_hi:[1,0]
	v_pk_mul_f32 v[196:197], v[144:145], s[12:13] op_sel_hi:[1,0]
	v_pk_mul_f32 v[198:199], v[134:135], s[12:13] op_sel_hi:[1,0]
	v_pk_mul_f32 v[200:201], v[136:137], s[12:13] op_sel_hi:[1,0]
	v_pk_mul_f32 v[142:143], v[142:143], v[138:139]
	v_pk_mul_f32 v[144:145], v[144:145], v[140:141]
	v_pk_mul_f32 v[134:135], v[134:135], v[130:131]
	v_pk_mul_f32 v[136:137], v[136:137], v[132:133]
	v_exp_f32_e32 v194, v194
	v_exp_f32_e32 v195, v195
	v_exp_f32_e32 v196, v196
	v_exp_f32_e32 v197, v197
	v_exp_f32_e32 v198, v198
	v_exp_f32_e32 v199, v199
	v_exp_f32_e32 v200, v200
	v_exp_f32_e32 v201, v201
	v_add_f32_e32 v194, 1.0, v194
	v_add_f32_e32 v195, 1.0, v195
	v_add_f32_e32 v196, 1.0, v196
	v_add_f32_e32 v197, 1.0, v197
	v_add_f32_e32 v198, 1.0, v198
	v_add_f32_e32 v199, 1.0, v199
	v_add_f32_e32 v200, 1.0, v200
	v_add_f32_e32 v201, 1.0, v201
	v_rcp_f32_e32 v194, v194
	v_rcp_f32_e32 v195, v195
	v_rcp_f32_e32 v196, v196
	v_rcp_f32_e32 v197, v197
	v_rcp_f32_e32 v198, v198
	v_rcp_f32_e32 v199, v199
	v_rcp_f32_e32 v200, v200
	v_rcp_f32_e32 v201, v201
	v_pk_mul_f32 v[142:143], v[142:143], v[194:195]
	v_pk_mul_f32 v[144:145], v[144:145], v[196:197]
	v_pk_mul_f32 v[134:135], v[134:135], v[198:199]
	v_pk_mul_f32 v[136:137], v[136:137], v[200:201]
	v_cvt_pk_bf16_f32 v138, v142, v143
	v_cvt_pk_bf16_f32 v139, v144, v145
	v_cvt_pk_bf16_f32 v140, v134, v135
	v_cvt_pk_bf16_f32 v141, v136, v137
	global_store_dwordx4 v[190:191], v[138:141], off
	v_add_co_u32_e32 v190, vcc, 0x16000, v190
	s_nop 1
	v_addc_co_u32_e32 v191, vcc, 0, v191, vcc
	s_waitcnt lgkmcnt(1)
	v_pk_fma_f32 v[126:127], v[146:147], v[192:193], v[126:127] op_sel_hi:[1,0,1] neg_lo:[1,0,0] neg_hi:[1,0,0]
	v_pk_fma_f32 v[128:129], v[148:149], v[192:193], v[128:129] op_sel_hi:[1,0,1] neg_lo:[1,0,0] neg_hi:[1,0,0]
	v_pk_fma_f32 v[118:119], v[150:151], v[192:193], v[118:119] op_sel_hi:[1,0,1] neg_lo:[1,0,0] neg_hi:[1,0,0]
	v_pk_fma_f32 v[120:121], v[152:153], v[192:193], v[120:121] op_sel_hi:[1,0,1] neg_lo:[1,0,0] neg_hi:[1,0,0]
	v_pk_fma_f32 v[122:123], v[174:175], v[192:193], v[122:123] op_sel_hi:[1,0,1] neg_lo:[1,0,0] neg_hi:[1,0,0]
	v_pk_fma_f32 v[124:125], v[176:177], v[192:193], v[124:125] op_sel_hi:[1,0,1] neg_lo:[1,0,0] neg_hi:[1,0,0]
	v_pk_fma_f32 v[114:115], v[178:179], v[192:193], v[114:115] op_sel_hi:[1,0,1] neg_lo:[1,0,0] neg_hi:[1,0,0]
	v_pk_fma_f32 v[116:117], v[180:181], v[192:193], v[116:117] op_sel_hi:[1,0,1] neg_lo:[1,0,0] neg_hi:[1,0,0]
	v_pk_fma_f32 v[126:127], v[192:193], v[126:127], v[182:183] op_sel:[1,0,0]
	v_pk_fma_f32 v[128:129], v[192:193], v[128:129], v[184:185] op_sel:[1,0,0]
	v_pk_fma_f32 v[118:119], v[192:193], v[118:119], v[66:67] op_sel:[1,0,0]
	v_pk_fma_f32 v[120:121], v[192:193], v[120:121], v[68:69] op_sel:[1,0,0]
	v_pk_fma_f32 v[122:123], v[192:193], v[122:123], v[70:71] op_sel:[1,0,0]
	v_pk_fma_f32 v[124:125], v[192:193], v[124:125], v[72:73] op_sel:[1,0,0]
	v_pk_fma_f32 v[114:115], v[192:193], v[114:115], v[50:51] op_sel:[1,0,0]
	v_pk_fma_f32 v[116:117], v[192:193], v[116:117], v[52:53] op_sel:[1,0,0]
	ds_read_b64 v[192:193], v189 offset:384
	v_pk_mul_f32 v[194:195], v[126:127], s[12:13] op_sel_hi:[1,0]
	v_pk_mul_f32 v[196:197], v[128:129], s[12:13] op_sel_hi:[1,0]
	v_pk_mul_f32 v[198:199], v[118:119], s[12:13] op_sel_hi:[1,0]
	v_pk_mul_f32 v[200:201], v[120:121], s[12:13] op_sel_hi:[1,0]
	v_pk_mul_f32 v[126:127], v[126:127], v[122:123]
	v_pk_mul_f32 v[128:129], v[128:129], v[124:125]
	v_pk_mul_f32 v[118:119], v[118:119], v[114:115]
	v_pk_mul_f32 v[120:121], v[120:121], v[116:117]
	v_exp_f32_e32 v194, v194
	v_exp_f32_e32 v195, v195
	v_exp_f32_e32 v196, v196
	v_exp_f32_e32 v197, v197
	v_exp_f32_e32 v198, v198
	v_exp_f32_e32 v199, v199
	v_exp_f32_e32 v200, v200
	v_exp_f32_e32 v201, v201
	v_add_f32_e32 v194, 1.0, v194
	v_add_f32_e32 v195, 1.0, v195
	v_add_f32_e32 v196, 1.0, v196
	v_add_f32_e32 v197, 1.0, v197
	v_add_f32_e32 v198, 1.0, v198
	v_add_f32_e32 v199, 1.0, v199
	v_add_f32_e32 v200, 1.0, v200
	v_add_f32_e32 v201, 1.0, v201
	v_rcp_f32_e32 v194, v194
	v_rcp_f32_e32 v195, v195
	v_rcp_f32_e32 v196, v196
	v_rcp_f32_e32 v197, v197
	v_rcp_f32_e32 v198, v198
	v_rcp_f32_e32 v199, v199
	v_rcp_f32_e32 v200, v200
	v_rcp_f32_e32 v201, v201
	v_pk_mul_f32 v[126:127], v[126:127], v[194:195]
	v_pk_mul_f32 v[128:129], v[128:129], v[196:197]
	v_pk_mul_f32 v[118:119], v[118:119], v[198:199]
	v_pk_mul_f32 v[120:121], v[120:121], v[200:201]
	v_cvt_pk_bf16_f32 v122, v126, v127
	v_cvt_pk_bf16_f32 v123, v128, v129
	v_cvt_pk_bf16_f32 v124, v118, v119
	v_cvt_pk_bf16_f32 v125, v120, v121
	global_store_dwordx4 v[190:191], v[122:125], off
	v_add_co_u32_e32 v190, vcc, 0x16000, v190
	s_nop 1
	v_addc_co_u32_e32 v191, vcc, 0, v191, vcc
	s_waitcnt lgkmcnt(1)
	v_pk_fma_f32 v[110:111], v[146:147], v[56:57], v[110:111] op_sel_hi:[1,0,1] neg_lo:[1,0,0] neg_hi:[1,0,0]
	v_pk_fma_f32 v[112:113], v[148:149], v[56:57], v[112:113] op_sel_hi:[1,0,1] neg_lo:[1,0,0] neg_hi:[1,0,0]
	v_pk_fma_f32 v[102:103], v[150:151], v[56:57], v[102:103] op_sel_hi:[1,0,1] neg_lo:[1,0,0] neg_hi:[1,0,0]
	v_pk_fma_f32 v[104:105], v[152:153], v[56:57], v[104:105] op_sel_hi:[1,0,1] neg_lo:[1,0,0] neg_hi:[1,0,0]
	v_pk_fma_f32 v[106:107], v[174:175], v[56:57], v[106:107] op_sel_hi:[1,0,1] neg_lo:[1,0,0] neg_hi:[1,0,0]
	v_pk_fma_f32 v[108:109], v[176:177], v[56:57], v[108:109] op_sel_hi:[1,0,1] neg_lo:[1,0,0] neg_hi:[1,0,0]
	v_pk_fma_f32 v[98:99], v[178:179], v[56:57], v[98:99] op_sel_hi:[1,0,1] neg_lo:[1,0,0] neg_hi:[1,0,0]
	v_pk_fma_f32 v[100:101], v[180:181], v[56:57], v[100:101] op_sel_hi:[1,0,1] neg_lo:[1,0,0] neg_hi:[1,0,0]
	v_pk_fma_f32 v[110:111], v[56:57], v[110:111], v[182:183] op_sel:[1,0,0]
	v_pk_fma_f32 v[112:113], v[56:57], v[112:113], v[184:185] op_sel:[1,0,0]
	v_pk_fma_f32 v[102:103], v[56:57], v[102:103], v[66:67] op_sel:[1,0,0]
	v_pk_fma_f32 v[104:105], v[56:57], v[104:105], v[68:69] op_sel:[1,0,0]
	v_pk_fma_f32 v[106:107], v[56:57], v[106:107], v[70:71] op_sel:[1,0,0]
	v_pk_fma_f32 v[108:109], v[56:57], v[108:109], v[72:73] op_sel:[1,0,0]
	v_pk_fma_f32 v[98:99], v[56:57], v[98:99], v[50:51] op_sel:[1,0,0]
	v_pk_fma_f32 v[100:101], v[56:57], v[100:101], v[52:53] op_sel:[1,0,0]
	ds_read_b64 v[56:57], v189 offset:1024
	v_pk_mul_f32 v[194:195], v[110:111], s[12:13] op_sel_hi:[1,0]
	v_pk_mul_f32 v[196:197], v[112:113], s[12:13] op_sel_hi:[1,0]
	v_pk_mul_f32 v[198:199], v[102:103], s[12:13] op_sel_hi:[1,0]
	v_pk_mul_f32 v[200:201], v[104:105], s[12:13] op_sel_hi:[1,0]
	v_pk_mul_f32 v[110:111], v[110:111], v[106:107]
	v_pk_mul_f32 v[112:113], v[112:113], v[108:109]
	v_pk_mul_f32 v[102:103], v[102:103], v[98:99]
	v_pk_mul_f32 v[104:105], v[104:105], v[100:101]
	v_exp_f32_e32 v194, v194
	v_exp_f32_e32 v195, v195
	v_exp_f32_e32 v196, v196
	v_exp_f32_e32 v197, v197
	v_exp_f32_e32 v198, v198
	v_exp_f32_e32 v199, v199
	v_exp_f32_e32 v200, v200
	v_exp_f32_e32 v201, v201
	v_add_f32_e32 v194, 1.0, v194
	v_add_f32_e32 v195, 1.0, v195
	v_add_f32_e32 v196, 1.0, v196
	v_add_f32_e32 v197, 1.0, v197
	v_add_f32_e32 v198, 1.0, v198
	v_add_f32_e32 v199, 1.0, v199
	v_add_f32_e32 v200, 1.0, v200
	v_add_f32_e32 v201, 1.0, v201
	v_rcp_f32_e32 v194, v194
	v_rcp_f32_e32 v195, v195
	v_rcp_f32_e32 v196, v196
	v_rcp_f32_e32 v197, v197
	v_rcp_f32_e32 v198, v198
	v_rcp_f32_e32 v199, v199
	v_rcp_f32_e32 v200, v200
	v_rcp_f32_e32 v201, v201
	v_pk_mul_f32 v[110:111], v[110:111], v[194:195]
	v_pk_mul_f32 v[112:113], v[112:113], v[196:197]
	v_pk_mul_f32 v[102:103], v[102:103], v[198:199]
	v_pk_mul_f32 v[104:105], v[104:105], v[200:201]
	v_cvt_pk_bf16_f32 v106, v110, v111
	v_cvt_pk_bf16_f32 v107, v112, v113
	v_cvt_pk_bf16_f32 v108, v102, v103
	v_cvt_pk_bf16_f32 v109, v104, v105
	global_store_dwordx4 v[190:191], v[106:109], off
	v_add_co_u32_e32 v190, vcc, 0x16000, v190
	s_nop 1
	v_addc_co_u32_e32 v191, vcc, 0, v191, vcc
	s_waitcnt lgkmcnt(1)
	v_pk_fma_f32 v[94:95], v[146:147], v[192:193], v[94:95] op_sel_hi:[1,0,1] neg_lo:[1,0,0] neg_hi:[1,0,0]
	v_pk_fma_f32 v[96:97], v[148:149], v[192:193], v[96:97] op_sel_hi:[1,0,1] neg_lo:[1,0,0] neg_hi:[1,0,0]
	v_pk_fma_f32 v[86:87], v[150:151], v[192:193], v[86:87] op_sel_hi:[1,0,1] neg_lo:[1,0,0] neg_hi:[1,0,0]
	v_pk_fma_f32 v[88:89], v[152:153], v[192:193], v[88:89] op_sel_hi:[1,0,1] neg_lo:[1,0,0] neg_hi:[1,0,0]
	v_pk_fma_f32 v[90:91], v[174:175], v[192:193], v[90:91] op_sel_hi:[1,0,1] neg_lo:[1,0,0] neg_hi:[1,0,0]
	v_pk_fma_f32 v[92:93], v[176:177], v[192:193], v[92:93] op_sel_hi:[1,0,1] neg_lo:[1,0,0] neg_hi:[1,0,0]
	v_pk_fma_f32 v[82:83], v[178:179], v[192:193], v[82:83] op_sel_hi:[1,0,1] neg_lo:[1,0,0] neg_hi:[1,0,0]
	v_pk_fma_f32 v[84:85], v[180:181], v[192:193], v[84:85] op_sel_hi:[1,0,1] neg_lo:[1,0,0] neg_hi:[1,0,0]
	v_pk_fma_f32 v[94:95], v[192:193], v[94:95], v[182:183] op_sel:[1,0,0]
	v_pk_fma_f32 v[96:97], v[192:193], v[96:97], v[184:185] op_sel:[1,0,0]
	v_pk_fma_f32 v[86:87], v[192:193], v[86:87], v[66:67] op_sel:[1,0,0]
	v_pk_fma_f32 v[88:89], v[192:193], v[88:89], v[68:69] op_sel:[1,0,0]
	v_pk_fma_f32 v[90:91], v[192:193], v[90:91], v[70:71] op_sel:[1,0,0]
	v_pk_fma_f32 v[92:93], v[192:193], v[92:93], v[72:73] op_sel:[1,0,0]
	v_pk_fma_f32 v[82:83], v[192:193], v[82:83], v[50:51] op_sel:[1,0,0]
	v_pk_fma_f32 v[84:85], v[192:193], v[84:85], v[52:53] op_sel:[1,0,0]
	ds_read_b64 v[192:193], v189 offset:1152
	v_pk_mul_f32 v[194:195], v[94:95], s[12:13] op_sel_hi:[1,0]
	v_pk_mul_f32 v[196:197], v[96:97], s[12:13] op_sel_hi:[1,0]
	v_pk_mul_f32 v[198:199], v[86:87], s[12:13] op_sel_hi:[1,0]
	v_pk_mul_f32 v[200:201], v[88:89], s[12:13] op_sel_hi:[1,0]
	v_pk_mul_f32 v[94:95], v[94:95], v[90:91]
	v_pk_mul_f32 v[96:97], v[96:97], v[92:93]
	v_pk_mul_f32 v[86:87], v[86:87], v[82:83]
	v_pk_mul_f32 v[88:89], v[88:89], v[84:85]
	v_exp_f32_e32 v194, v194
	v_exp_f32_e32 v195, v195
	v_exp_f32_e32 v196, v196
	v_exp_f32_e32 v197, v197
	v_exp_f32_e32 v198, v198
	v_exp_f32_e32 v199, v199
	v_exp_f32_e32 v200, v200
	v_exp_f32_e32 v201, v201
	v_add_f32_e32 v194, 1.0, v194
	v_add_f32_e32 v195, 1.0, v195
	v_add_f32_e32 v196, 1.0, v196
	v_add_f32_e32 v197, 1.0, v197
	v_add_f32_e32 v198, 1.0, v198
	v_add_f32_e32 v199, 1.0, v199
	v_add_f32_e32 v200, 1.0, v200
	v_add_f32_e32 v201, 1.0, v201
	v_rcp_f32_e32 v194, v194
	v_rcp_f32_e32 v195, v195
	v_rcp_f32_e32 v196, v196
	v_rcp_f32_e32 v197, v197
	v_rcp_f32_e32 v198, v198
	v_rcp_f32_e32 v199, v199
	v_rcp_f32_e32 v200, v200
	v_rcp_f32_e32 v201, v201
	v_pk_mul_f32 v[94:95], v[94:95], v[194:195]
	v_pk_mul_f32 v[96:97], v[96:97], v[196:197]
	v_pk_mul_f32 v[86:87], v[86:87], v[198:199]
	v_pk_mul_f32 v[88:89], v[88:89], v[200:201]
	v_cvt_pk_bf16_f32 v90, v94, v95
	v_cvt_pk_bf16_f32 v91, v96, v97
	v_cvt_pk_bf16_f32 v92, v86, v87
	v_cvt_pk_bf16_f32 v93, v88, v89
	global_store_dwordx4 v[190:191], v[90:93], off
	v_add_co_u32_e32 v190, vcc, 0x6e000, v190
	s_nop 1
	v_addc_co_u32_e32 v191, vcc, 0, v191, vcc
	s_waitcnt lgkmcnt(1)
	v_pk_fma_f32 v[78:79], v[146:147], v[56:57], v[78:79] op_sel_hi:[1,0,1] neg_lo:[1,0,0] neg_hi:[1,0,0]
	v_pk_fma_f32 v[80:81], v[148:149], v[56:57], v[80:81] op_sel_hi:[1,0,1] neg_lo:[1,0,0] neg_hi:[1,0,0]
	v_pk_fma_f32 v[62:63], v[150:151], v[56:57], v[62:63] op_sel_hi:[1,0,1] neg_lo:[1,0,0] neg_hi:[1,0,0]
	v_pk_fma_f32 v[64:65], v[152:153], v[56:57], v[64:65] op_sel_hi:[1,0,1] neg_lo:[1,0,0] neg_hi:[1,0,0]
	v_pk_fma_f32 v[74:75], v[174:175], v[56:57], v[74:75] op_sel_hi:[1,0,1] neg_lo:[1,0,0] neg_hi:[1,0,0]
	v_pk_fma_f32 v[76:77], v[176:177], v[56:57], v[76:77] op_sel_hi:[1,0,1] neg_lo:[1,0,0] neg_hi:[1,0,0]
	v_pk_fma_f32 v[58:59], v[178:179], v[56:57], v[58:59] op_sel_hi:[1,0,1] neg_lo:[1,0,0] neg_hi:[1,0,0]
	v_pk_fma_f32 v[60:61], v[180:181], v[56:57], v[60:61] op_sel_hi:[1,0,1] neg_lo:[1,0,0] neg_hi:[1,0,0]
	v_pk_fma_f32 v[78:79], v[56:57], v[78:79], v[182:183] op_sel:[1,0,0]
	v_pk_fma_f32 v[80:81], v[56:57], v[80:81], v[184:185] op_sel:[1,0,0]
	v_pk_fma_f32 v[62:63], v[56:57], v[62:63], v[66:67] op_sel:[1,0,0]
	v_pk_fma_f32 v[64:65], v[56:57], v[64:65], v[68:69] op_sel:[1,0,0]
	v_pk_fma_f32 v[74:75], v[56:57], v[74:75], v[70:71] op_sel:[1,0,0]
	v_pk_fma_f32 v[76:77], v[56:57], v[76:77], v[72:73] op_sel:[1,0,0]
	v_pk_fma_f32 v[58:59], v[56:57], v[58:59], v[50:51] op_sel:[1,0,0]
	v_pk_fma_f32 v[60:61], v[56:57], v[60:61], v[52:53] op_sel:[1,0,0]
	ds_read_b64 v[56:57], v189 offset:1280
	v_pk_mul_f32 v[194:195], v[78:79], s[12:13] op_sel_hi:[1,0]
	v_pk_mul_f32 v[196:197], v[80:81], s[12:13] op_sel_hi:[1,0]
	v_pk_mul_f32 v[198:199], v[62:63], s[12:13] op_sel_hi:[1,0]
	v_pk_mul_f32 v[200:201], v[64:65], s[12:13] op_sel_hi:[1,0]
	v_pk_mul_f32 v[78:79], v[78:79], v[74:75]
	v_pk_mul_f32 v[80:81], v[80:81], v[76:77]
	v_pk_mul_f32 v[62:63], v[62:63], v[58:59]
	v_pk_mul_f32 v[64:65], v[64:65], v[60:61]
	v_exp_f32_e32 v194, v194
	v_exp_f32_e32 v195, v195
	v_exp_f32_e32 v196, v196
	v_exp_f32_e32 v197, v197
	v_exp_f32_e32 v198, v198
	v_exp_f32_e32 v199, v199
	v_exp_f32_e32 v200, v200
	v_exp_f32_e32 v201, v201
	v_add_f32_e32 v194, 1.0, v194
	v_add_f32_e32 v195, 1.0, v195
	v_add_f32_e32 v196, 1.0, v196
	v_add_f32_e32 v197, 1.0, v197
	v_add_f32_e32 v198, 1.0, v198
	v_add_f32_e32 v199, 1.0, v199
	v_add_f32_e32 v200, 1.0, v200
	v_add_f32_e32 v201, 1.0, v201
	v_rcp_f32_e32 v194, v194
	v_rcp_f32_e32 v195, v195
	v_rcp_f32_e32 v196, v196
	v_rcp_f32_e32 v197, v197
	v_rcp_f32_e32 v198, v198
	v_rcp_f32_e32 v199, v199
	v_rcp_f32_e32 v200, v200
	v_rcp_f32_e32 v201, v201
	v_pk_mul_f32 v[78:79], v[78:79], v[194:195]
	v_pk_mul_f32 v[80:81], v[80:81], v[196:197]
	v_pk_mul_f32 v[62:63], v[62:63], v[198:199]
	v_pk_mul_f32 v[64:65], v[64:65], v[200:201]
	v_cvt_pk_bf16_f32 v74, v78, v79
	v_cvt_pk_bf16_f32 v75, v80, v81
	v_cvt_pk_bf16_f32 v76, v62, v63
	v_cvt_pk_bf16_f32 v77, v64, v65
	global_store_dwordx4 v[190:191], v[74:77], off
	v_add_co_u32_e32 v190, vcc, 0x16000, v190
	s_nop 1
	v_addc_co_u32_e32 v191, vcc, 0, v191, vcc
	s_waitcnt lgkmcnt(1)
	v_pk_fma_f32 v[46:47], v[146:147], v[192:193], v[46:47] op_sel_hi:[1,0,1] neg_lo:[1,0,0] neg_hi:[1,0,0]
	v_pk_fma_f32 v[48:49], v[148:149], v[192:193], v[48:49] op_sel_hi:[1,0,1] neg_lo:[1,0,0] neg_hi:[1,0,0]
	v_pk_fma_f32 v[38:39], v[150:151], v[192:193], v[38:39] op_sel_hi:[1,0,1] neg_lo:[1,0,0] neg_hi:[1,0,0]
	v_pk_fma_f32 v[40:41], v[152:153], v[192:193], v[40:41] op_sel_hi:[1,0,1] neg_lo:[1,0,0] neg_hi:[1,0,0]
	v_pk_fma_f32 v[42:43], v[174:175], v[192:193], v[42:43] op_sel_hi:[1,0,1] neg_lo:[1,0,0] neg_hi:[1,0,0]
	v_pk_fma_f32 v[44:45], v[176:177], v[192:193], v[44:45] op_sel_hi:[1,0,1] neg_lo:[1,0,0] neg_hi:[1,0,0]
	v_pk_fma_f32 v[34:35], v[178:179], v[192:193], v[34:35] op_sel_hi:[1,0,1] neg_lo:[1,0,0] neg_hi:[1,0,0]
	v_pk_fma_f32 v[36:37], v[180:181], v[192:193], v[36:37] op_sel_hi:[1,0,1] neg_lo:[1,0,0] neg_hi:[1,0,0]
	v_pk_fma_f32 v[46:47], v[192:193], v[46:47], v[182:183] op_sel:[1,0,0]
	v_pk_fma_f32 v[48:49], v[192:193], v[48:49], v[184:185] op_sel:[1,0,0]
	v_pk_fma_f32 v[38:39], v[192:193], v[38:39], v[66:67] op_sel:[1,0,0]
	v_pk_fma_f32 v[40:41], v[192:193], v[40:41], v[68:69] op_sel:[1,0,0]
	v_pk_fma_f32 v[42:43], v[192:193], v[42:43], v[70:71] op_sel:[1,0,0]
	v_pk_fma_f32 v[44:45], v[192:193], v[44:45], v[72:73] op_sel:[1,0,0]
	v_pk_fma_f32 v[34:35], v[192:193], v[34:35], v[50:51] op_sel:[1,0,0]
	v_pk_fma_f32 v[36:37], v[192:193], v[36:37], v[52:53] op_sel:[1,0,0]
	ds_read_b64 v[192:193], v189 offset:1408
	v_pk_mul_f32 v[194:195], v[46:47], s[12:13] op_sel_hi:[1,0]
	v_pk_mul_f32 v[196:197], v[48:49], s[12:13] op_sel_hi:[1,0]
	v_pk_mul_f32 v[198:199], v[38:39], s[12:13] op_sel_hi:[1,0]
	v_pk_mul_f32 v[200:201], v[40:41], s[12:13] op_sel_hi:[1,0]
	v_pk_mul_f32 v[46:47], v[46:47], v[42:43]
	v_pk_mul_f32 v[48:49], v[48:49], v[44:45]
	v_pk_mul_f32 v[38:39], v[38:39], v[34:35]
	v_pk_mul_f32 v[40:41], v[40:41], v[36:37]
	v_exp_f32_e32 v194, v194
	v_exp_f32_e32 v195, v195
	v_exp_f32_e32 v196, v196
	v_exp_f32_e32 v197, v197
	v_exp_f32_e32 v198, v198
	v_exp_f32_e32 v199, v199
	v_exp_f32_e32 v200, v200
	v_exp_f32_e32 v201, v201
	v_add_f32_e32 v194, 1.0, v194
	v_add_f32_e32 v195, 1.0, v195
	v_add_f32_e32 v196, 1.0, v196
	v_add_f32_e32 v197, 1.0, v197
	v_add_f32_e32 v198, 1.0, v198
	v_add_f32_e32 v199, 1.0, v199
	v_add_f32_e32 v200, 1.0, v200
	v_add_f32_e32 v201, 1.0, v201
	v_rcp_f32_e32 v194, v194
	v_rcp_f32_e32 v195, v195
	v_rcp_f32_e32 v196, v196
	v_rcp_f32_e32 v197, v197
	v_rcp_f32_e32 v198, v198
	v_rcp_f32_e32 v199, v199
	v_rcp_f32_e32 v200, v200
	v_rcp_f32_e32 v201, v201
	v_pk_mul_f32 v[46:47], v[46:47], v[194:195]
	v_pk_mul_f32 v[48:49], v[48:49], v[196:197]
	v_pk_mul_f32 v[38:39], v[38:39], v[198:199]
	v_pk_mul_f32 v[40:41], v[40:41], v[200:201]
	v_cvt_pk_bf16_f32 v42, v46, v47
	v_cvt_pk_bf16_f32 v43, v48, v49
	v_cvt_pk_bf16_f32 v44, v38, v39
	v_cvt_pk_bf16_f32 v45, v40, v41
	global_store_dwordx4 v[190:191], v[42:45], off
	v_add_co_u32_e32 v190, vcc, 0x16000, v190
	s_nop 1
	v_addc_co_u32_e32 v191, vcc, 0, v191, vcc
	s_waitcnt lgkmcnt(1)
	v_pk_fma_f32 v[30:31], v[146:147], v[56:57], v[30:31] op_sel_hi:[1,0,1] neg_lo:[1,0,0] neg_hi:[1,0,0]
	v_pk_fma_f32 v[32:33], v[148:149], v[56:57], v[32:33] op_sel_hi:[1,0,1] neg_lo:[1,0,0] neg_hi:[1,0,0]
	v_pk_fma_f32 v[22:23], v[150:151], v[56:57], v[22:23] op_sel_hi:[1,0,1] neg_lo:[1,0,0] neg_hi:[1,0,0]
	v_pk_fma_f32 v[24:25], v[152:153], v[56:57], v[24:25] op_sel_hi:[1,0,1] neg_lo:[1,0,0] neg_hi:[1,0,0]
	v_pk_fma_f32 v[26:27], v[174:175], v[56:57], v[26:27] op_sel_hi:[1,0,1] neg_lo:[1,0,0] neg_hi:[1,0,0]
	v_pk_fma_f32 v[28:29], v[176:177], v[56:57], v[28:29] op_sel_hi:[1,0,1] neg_lo:[1,0,0] neg_hi:[1,0,0]
	v_pk_fma_f32 v[18:19], v[178:179], v[56:57], v[18:19] op_sel_hi:[1,0,1] neg_lo:[1,0,0] neg_hi:[1,0,0]
	v_pk_fma_f32 v[20:21], v[180:181], v[56:57], v[20:21] op_sel_hi:[1,0,1] neg_lo:[1,0,0] neg_hi:[1,0,0]
	v_pk_fma_f32 v[30:31], v[56:57], v[30:31], v[182:183] op_sel:[1,0,0]
	v_pk_fma_f32 v[32:33], v[56:57], v[32:33], v[184:185] op_sel:[1,0,0]
	v_pk_fma_f32 v[22:23], v[56:57], v[22:23], v[66:67] op_sel:[1,0,0]
	v_pk_fma_f32 v[24:25], v[56:57], v[24:25], v[68:69] op_sel:[1,0,0]
	v_pk_fma_f32 v[26:27], v[56:57], v[26:27], v[70:71] op_sel:[1,0,0]
	v_pk_fma_f32 v[28:29], v[56:57], v[28:29], v[72:73] op_sel:[1,0,0]
	v_pk_fma_f32 v[18:19], v[56:57], v[18:19], v[50:51] op_sel:[1,0,0]
	v_pk_fma_f32 v[20:21], v[56:57], v[20:21], v[52:53] op_sel:[1,0,0]
	v_pk_mul_f32 v[194:195], v[30:31], s[12:13] op_sel_hi:[1,0]
	v_pk_mul_f32 v[196:197], v[32:33], s[12:13] op_sel_hi:[1,0]
	v_pk_mul_f32 v[198:199], v[22:23], s[12:13] op_sel_hi:[1,0]
	v_pk_mul_f32 v[200:201], v[24:25], s[12:13] op_sel_hi:[1,0]
	v_pk_mul_f32 v[30:31], v[30:31], v[26:27]
	v_pk_mul_f32 v[32:33], v[32:33], v[28:29]
	v_pk_mul_f32 v[22:23], v[22:23], v[18:19]
	v_pk_mul_f32 v[24:25], v[24:25], v[20:21]
	v_exp_f32_e32 v194, v194
	v_exp_f32_e32 v195, v195
	v_exp_f32_e32 v196, v196
	v_exp_f32_e32 v197, v197
	v_exp_f32_e32 v198, v198
	v_exp_f32_e32 v199, v199
	v_exp_f32_e32 v200, v200
	v_exp_f32_e32 v201, v201
	v_add_f32_e32 v194, 1.0, v194
	v_add_f32_e32 v195, 1.0, v195
	v_add_f32_e32 v196, 1.0, v196
	v_add_f32_e32 v197, 1.0, v197
	v_add_f32_e32 v198, 1.0, v198
	v_add_f32_e32 v199, 1.0, v199
	v_add_f32_e32 v200, 1.0, v200
	v_add_f32_e32 v201, 1.0, v201
	v_rcp_f32_e32 v194, v194
	v_rcp_f32_e32 v195, v195
	v_rcp_f32_e32 v196, v196
	v_rcp_f32_e32 v197, v197
	v_rcp_f32_e32 v198, v198
	v_rcp_f32_e32 v199, v199
	v_rcp_f32_e32 v200, v200
	v_rcp_f32_e32 v201, v201
	v_pk_mul_f32 v[30:31], v[30:31], v[194:195]
	v_pk_mul_f32 v[32:33], v[32:33], v[196:197]
	v_pk_mul_f32 v[22:23], v[22:23], v[198:199]
	v_pk_mul_f32 v[24:25], v[24:25], v[200:201]
	v_cvt_pk_bf16_f32 v26, v30, v31
	v_cvt_pk_bf16_f32 v27, v32, v33
	v_cvt_pk_bf16_f32 v28, v22, v23
	v_cvt_pk_bf16_f32 v29, v24, v25
	global_store_dwordx4 v[190:191], v[26:29], off
	v_add_co_u32_e32 v190, vcc, 0x16000, v190
	s_nop 1
	v_addc_co_u32_e32 v191, vcc, 0, v191, vcc
	s_waitcnt lgkmcnt(0)
	v_pk_fma_f32 v[14:15], v[146:147], v[192:193], v[14:15] op_sel_hi:[1,0,1] neg_lo:[1,0,0] neg_hi:[1,0,0]
	v_pk_fma_f32 v[16:17], v[148:149], v[192:193], v[16:17] op_sel_hi:[1,0,1] neg_lo:[1,0,0] neg_hi:[1,0,0]
	v_pk_fma_f32 v[6:7], v[150:151], v[192:193], v[6:7] op_sel_hi:[1,0,1] neg_lo:[1,0,0] neg_hi:[1,0,0]
	v_pk_fma_f32 v[8:9], v[152:153], v[192:193], v[8:9] op_sel_hi:[1,0,1] neg_lo:[1,0,0] neg_hi:[1,0,0]
	v_pk_fma_f32 v[10:11], v[174:175], v[192:193], v[10:11] op_sel_hi:[1,0,1] neg_lo:[1,0,0] neg_hi:[1,0,0]
	v_pk_fma_f32 v[12:13], v[176:177], v[192:193], v[12:13] op_sel_hi:[1,0,1] neg_lo:[1,0,0] neg_hi:[1,0,0]
	v_pk_fma_f32 v[2:3], v[178:179], v[192:193], v[2:3] op_sel_hi:[1,0,1] neg_lo:[1,0,0] neg_hi:[1,0,0]
	v_pk_fma_f32 v[4:5], v[180:181], v[192:193], v[4:5] op_sel_hi:[1,0,1] neg_lo:[1,0,0] neg_hi:[1,0,0]
	v_pk_fma_f32 v[14:15], v[192:193], v[14:15], v[182:183] op_sel:[1,0,0]
	v_pk_fma_f32 v[16:17], v[192:193], v[16:17], v[184:185] op_sel:[1,0,0]
	v_pk_fma_f32 v[6:7], v[192:193], v[6:7], v[66:67] op_sel:[1,0,0]
	v_pk_fma_f32 v[8:9], v[192:193], v[8:9], v[68:69] op_sel:[1,0,0]
	v_pk_fma_f32 v[10:11], v[192:193], v[10:11], v[70:71] op_sel:[1,0,0]
	v_pk_fma_f32 v[12:13], v[192:193], v[12:13], v[72:73] op_sel:[1,0,0]
	v_pk_fma_f32 v[2:3], v[192:193], v[2:3], v[50:51] op_sel:[1,0,0]
	v_pk_fma_f32 v[4:5], v[192:193], v[4:5], v[52:53] op_sel:[1,0,0]
	v_pk_mul_f32 v[194:195], v[14:15], s[12:13] op_sel_hi:[1,0]
	v_pk_mul_f32 v[196:197], v[16:17], s[12:13] op_sel_hi:[1,0]
	v_pk_mul_f32 v[198:199], v[6:7], s[12:13] op_sel_hi:[1,0]
	v_pk_mul_f32 v[200:201], v[8:9], s[12:13] op_sel_hi:[1,0]
	v_pk_mul_f32 v[14:15], v[14:15], v[10:11]
	v_pk_mul_f32 v[16:17], v[16:17], v[12:13]
	v_pk_mul_f32 v[6:7], v[6:7], v[2:3]
	v_pk_mul_f32 v[8:9], v[8:9], v[4:5]
	v_exp_f32_e32 v194, v194
	v_exp_f32_e32 v195, v195
	v_exp_f32_e32 v196, v196
	v_exp_f32_e32 v197, v197
	v_exp_f32_e32 v198, v198
	v_exp_f32_e32 v199, v199
	v_exp_f32_e32 v200, v200
	v_exp_f32_e32 v201, v201
	v_add_f32_e32 v194, 1.0, v194
	v_add_f32_e32 v195, 1.0, v195
	v_add_f32_e32 v196, 1.0, v196
	v_add_f32_e32 v197, 1.0, v197
	v_add_f32_e32 v198, 1.0, v198
	v_add_f32_e32 v199, 1.0, v199
	v_add_f32_e32 v200, 1.0, v200
	v_add_f32_e32 v201, 1.0, v201
	v_rcp_f32_e32 v194, v194
	v_rcp_f32_e32 v195, v195
	v_rcp_f32_e32 v196, v196
	v_rcp_f32_e32 v197, v197
	v_rcp_f32_e32 v198, v198
	v_rcp_f32_e32 v199, v199
	v_rcp_f32_e32 v200, v200
	v_rcp_f32_e32 v201, v201
	v_pk_mul_f32 v[14:15], v[14:15], v[194:195]
	v_pk_mul_f32 v[16:17], v[16:17], v[196:197]
	v_pk_mul_f32 v[6:7], v[6:7], v[198:199]
	v_pk_mul_f32 v[8:9], v[8:9], v[200:201]
	v_cvt_pk_bf16_f32 v10, v14, v15
	v_cvt_pk_bf16_f32 v11, v16, v17
	v_cvt_pk_bf16_f32 v12, v6, v7
	v_cvt_pk_bf16_f32 v13, v8, v9
	global_store_dwordx4 v[190:191], v[10:13], off
	s_mov_b64 s[56:57], -1
	s_andn2_b64 vcc, exec, s[38:39]
	s_cbranch_vccnz .LBB0_299
	s_andn2_b64 vcc, exec, s[40:41]
	s_cbranch_vccnz .LBB0_298
	s_barrier
	s_branch .LBB0_298

.LBB0_398:
	v_lshl_add_u32 v184, s72, 8, v163
	v_lshl_or_b32 v182, s58, 8, v210
	s_mov_b64 s[42:43], -1
	s_cmp_gt_i32 s16, -1
	v_ashrrev_i32_e32 v183, 31, v182
	v_ashrrev_i32_e32 v185, 31, v184
	s_mov_b32 s88, s95
	s_mov_b32 s95, s35
	s_mov_b32 s35, s18
	s_cbranch_scc1 .LBB0_405
	v_or_b32_e32 v188, 16, v184
	v_lshl_add_u64 v[186:187], v[182:183], 1, s[8:9]
	v_lshlrev_b64 v[196:197], 11, v[184:185]
	v_ashrrev_i32_e32 v189, 31, v188
	v_lshl_add_u64 v[130:131], v[186:187], 0, v[196:197]
	v_lshlrev_b64 v[190:191], 11, v[188:189]
	global_load_dwordx4 v[154:157], v[130:131], off
	global_load_dwordx4 v[138:141], v[130:131], off offset:256
	v_lshl_add_u64 v[130:131], v[186:187], 0, v[190:191]
	global_load_dwordx4 v[134:137], v[130:131], off
	s_nop 0
	global_load_dwordx4 v[130:133], v[130:131], off offset:256
	s_lshl_b32 s7, s7, 12
	s_and_b32 s7, s7, 0x1000
	s_add_i32 s7, s7, 0
	s_add_i32 s7, s7, 0x20000
	v_mov_b32_e32 v142, 1.0
	v_mov_b32_e32 v150, 0
	s_and_b64 vcc, exec, s[52:53]
	v_add_u32_e32 v213, s7, v209
	v_mov_b32_e32 v194, 0
	v_mov_b32_e32 v192, 1.0
	s_cbranch_vccz .LBB0_401
	ds_read_b64 v[194:195], v213
	s_waitcnt lgkmcnt(0)
	v_mov_b32_e32 v192, v195

.LBB0_403:
	s_waitcnt vmcnt(0)
	v_lshlrev_b32_e32 v1, 16, v154
	v_and_b32_e32 v154, 0xffff0000, v154
	v_lshlrev_b32_e32 v193, 16, v155
	v_and_b32_e32 v195, 0xffff0000, v155
	v_lshlrev_b32_e32 v202, 16, v156
	v_and_b32_e32 v203, 0xffff0000, v156
	v_lshlrev_b32_e32 v204, 16, v157
	v_and_b32_e32 v205, 0xffff0000, v157
	v_sub_f32_e32 v155, v154, v194
	v_sub_f32_e32 v154, v1, v194
	v_sub_f32_e32 v157, v195, v194
	v_sub_f32_e32 v156, v193, v194
	v_pk_mul_f32 v[156:157], v[192:193], v[156:157] op_sel_hi:[0,1]
	v_pk_mul_f32 v[154:155], v[192:193], v[154:155] op_sel_hi:[0,1]
	s_waitcnt lgkmcnt(1)
	v_pk_fma_f32 v[142:143], v[154:155], v[142:143], v[150:151]
	v_pk_fma_f32 v[144:145], v[156:157], v[144:145], v[152:153]
	v_pk_fma_f32 v[200:201], v[142:143], s[34:35], v[126:127] op_sel_hi:[1,0,1]
	v_pk_fma_f32 v[198:199], v[144:145], s[34:35], v[128:129] op_sel_hi:[1,0,1]
	v_sub_f32_e32 v143, v203, v194
	v_sub_f32_e32 v142, v202, v194
	v_sub_f32_e32 v145, v205, v194
	v_sub_f32_e32 v144, v204, v194
	v_pk_mul_f32 v[144:145], v[192:193], v[144:145] op_sel_hi:[0,1]
	v_pk_mul_f32 v[142:143], v[192:193], v[142:143] op_sel_hi:[0,1]
	s_waitcnt lgkmcnt(0)
	v_pk_fma_f32 v[142:143], v[142:143], v[146:147], v[158:159]
	v_pk_fma_f32 v[144:145], v[144:145], v[148:149], v[160:161]
	v_lshl_add_u64 v[146:147], s[8:9], 0, v[196:197]
	v_pk_fma_f32 v[160:161], v[144:145], s[34:35], v[124:125] op_sel_hi:[1,0,1]
	v_pk_fma_f32 v[202:203], v[142:143], s[34:35], v[122:123] op_sel_hi:[1,0,1]
	v_lshl_add_u64 v[158:159], v[182:183], 1, v[146:147]
	s_and_b64 vcc, exec, s[42:43]
	v_cvt_pk_bf16_f32 v142, v200, v201
	v_cvt_pk_bf16_f32 v143, v198, v199
	v_cvt_pk_bf16_f32 v144, v202, v203
	v_cvt_pk_bf16_f32 v145, v160, v161
	global_store_dwordx4 v[158:159], v[142:145], off
	s_cbranch_vccnz .LBB0_407
	ds_read_b128 v[150:153], v212 offset:2560
	ds_read_b128 v[142:145], v212 offset:2576
	ds_read_b128 v[154:157], v212 offset:3584
	ds_read_b128 v[146:149], v212 offset:3600
	s_branch .LBB0_408

.LBB0_419:
	s_or_b64 exec, exec, s[72:73]
	v_or_b32_e32 v192, 32, v184
	v_ashrrev_i32_e32 v193, 31, v192
	v_or_b32_e32 v188, 48, v184
	v_lshlrev_b64 v[198:199], 11, v[192:193]
	v_ashrrev_i32_e32 v189, 31, v188
	v_lshl_add_u64 v[130:131], v[186:187], 0, v[198:199]
	v_lshlrev_b64 v[190:191], 11, v[188:189]
	global_load_dwordx4 v[158:161], v[130:131], off
	global_load_dwordx4 v[138:141], v[130:131], off offset:256
	v_lshl_add_u64 v[130:131], v[186:187], 0, v[190:191]
	global_load_dwordx4 v[134:137], v[130:131], off
	s_waitcnt lgkmcnt(0)
	global_load_dwordx4 v[130:133], v[130:131], off offset:256
	v_mov_b32_e32 v146, 1.0
	v_mov_b32_e32 v154, 0
	s_and_b64 vcc, exec, s[42:43]
	v_mov_b32_e32 v196, 0
	v_mov_b32_e32 v194, 1.0
	s_cbranch_vccnz .LBB0_421
	ds_read_b64 v[196:197], v213 offset:256
	s_waitcnt lgkmcnt(0)
	v_mov_b32_e32 v194, v197

.LBB0_423:
	s_waitcnt vmcnt(3)
	v_lshlrev_b32_e32 v1, 16, v158
	v_and_b32_e32 v158, 0xffff0000, v158
	v_lshlrev_b32_e32 v195, 16, v159
	v_and_b32_e32 v197, 0xffff0000, v159
	v_lshlrev_b32_e32 v202, 16, v160
	v_and_b32_e32 v203, 0xffff0000, v160
	v_lshlrev_b32_e32 v204, 16, v161
	v_and_b32_e32 v205, 0xffff0000, v161
	v_sub_f32_e32 v159, v158, v196
	v_sub_f32_e32 v158, v1, v196
	v_sub_f32_e32 v161, v197, v196
	v_sub_f32_e32 v160, v195, v196
	v_pk_mul_f32 v[160:161], v[194:195], v[160:161] op_sel_hi:[0,1]
	v_pk_mul_f32 v[158:159], v[194:195], v[158:159] op_sel_hi:[0,1]
	s_waitcnt lgkmcnt(1)
	v_pk_fma_f32 v[146:147], v[158:159], v[146:147], v[154:155]
	v_pk_fma_f32 v[148:149], v[160:161], v[148:149], v[156:157]
	v_pk_fma_f32 v[200:201], v[146:147], s[34:35], v[102:103] op_sel_hi:[1,0,1]
	v_pk_fma_f32 v[160:161], v[148:149], s[34:35], v[104:105] op_sel_hi:[1,0,1]
	v_sub_f32_e32 v147, v203, v196
	v_sub_f32_e32 v146, v202, v196
	v_sub_f32_e32 v149, v205, v196
	v_sub_f32_e32 v148, v204, v196
	v_pk_mul_f32 v[148:149], v[194:195], v[148:149] op_sel_hi:[0,1]
	v_pk_mul_f32 v[146:147], v[194:195], v[146:147] op_sel_hi:[0,1]
	s_waitcnt lgkmcnt(0)
	v_pk_fma_f32 v[142:143], v[146:147], v[142:143], v[150:151]
	v_pk_fma_f32 v[144:145], v[148:149], v[144:145], v[152:153]
	v_lshl_add_u64 v[146:147], s[8:9], 0, v[198:199]
	v_pk_fma_f32 v[202:203], v[144:145], s[34:35], v[100:101] op_sel_hi:[1,0,1]
	v_pk_fma_f32 v[204:205], v[142:143], s[34:35], v[98:99] op_sel_hi:[1,0,1]
	v_lshl_add_u64 v[158:159], v[182:183], 1, v[146:147]
	s_and_b64 vcc, exec, s[42:43]
	v_cvt_pk_bf16_f32 v142, v200, v201
	v_cvt_pk_bf16_f32 v143, v160, v161
	v_cvt_pk_bf16_f32 v144, v204, v205
	v_cvt_pk_bf16_f32 v145, v202, v203
	global_store_dwordx4 v[158:159], v[142:145], off
	s_cbranch_vccnz .LBB0_425
	ds_read_b128 v[150:153], v212 offset:2560
	ds_read_b128 v[142:145], v212 offset:2576
	ds_read_b128 v[154:157], v212 offset:3584
	ds_read_b128 v[146:149], v212 offset:3600
	s_branch .LBB0_426

.LBB0_426:
	v_mov_b32_e32 v198, v201
	v_mov_b32_e32 v199, v160
	v_mov_b32_e32 v216, v200
	v_mov_b32_e32 v217, v161
	v_pk_add_f32 v[198:199], v[198:199], v[216:217]
	v_mul_f32_e32 v216, v200, v200
	v_pk_fma_f32 v[200:201], v[200:201], v[200:201], v[216:217] op_sel_hi:[1,1,0]
	v_mul_f32_e32 v1, v204, v204
	v_mul_f32_e32 v200, v160, v160
	v_pk_fma_f32 v[160:161], v[160:161], v[160:161], v[200:201] op_sel_hi:[1,1,0]
	v_mov_b32_e32 v200, v202
	v_mov_b32_e32 v160, v203
	v_pk_add_f32 v[160:161], v[200:201], v[160:161]
	v_pk_add_f32 v[200:201], v[204:205], v[204:205] op_sel:[1,0]
	v_pk_mul_f32 v[204:205], v[204:205], v[204:205]
	v_pk_add_f32 v[198:199], v[198:199], v[198:199] op_sel:[0,1] op_sel_hi:[1,0]
	v_mov_b32_e32 v201, v205
	v_mov_b32_e32 v199, v1
	v_pk_add_f32 v[198:199], v[200:201], v[198:199]
	s_waitcnt vmcnt(3)
	v_lshlrev_b32_e32 v197, 16, v139
	v_pk_add_f32 v[160:161], v[198:199], v[160:161]
	v_mul_f32_e32 v198, v202, v202
	v_pk_fma_f32 v[198:199], v[202:203], v[202:203], v[198:199] op_sel_hi:[1,1,0]
	v_lshlrev_b32_e32 v200, 16, v140
	v_mov_b32_e32 v1, v199
	v_and_b32_e32 v198, 0xffff0000, v139
	v_pk_add_f32 v[160:161], v[160:161], v[0:1]
	v_lshlrev_b32_e32 v1, 16, v138
	v_and_b32_e32 v138, 0xffff0000, v138
	v_and_b32_e32 v201, 0xffff0000, v140
	v_lshlrev_b32_e32 v202, 16, v141
	v_and_b32_e32 v203, 0xffff0000, v141
	v_sub_f32_e32 v141, v198, v196
	v_sub_f32_e32 v140, v197, v196
	v_mov_b32_e32 v198, v194
	v_mov_b32_e32 v199, v194
	v_mov_b32_e32 v195, v194
	v_sub_f32_e32 v139, v138, v196
	v_sub_f32_e32 v138, v1, v196
	v_pk_mul_f32 v[140:141], v[198:199], v[140:141]
	v_pk_mul_f32 v[138:139], v[194:195], v[138:139]
	s_waitcnt lgkmcnt(1)
	v_pk_fma_f32 v[140:141], v[140:141], v[152:153], v[156:157]
	v_pk_fma_f32 v[138:139], v[138:139], v[150:151], v[154:155]
	v_pk_fma_f32 v[150:151], v[140:141], s[34:35], v[80:81] op_sel_hi:[1,0,1]
	v_sub_f32_e32 v141, v201, v196
	v_sub_f32_e32 v140, v200, v196
	v_sub_f32_e32 v153, v203, v196
	v_sub_f32_e32 v152, v202, v196
	v_pk_mul_f32 v[152:153], v[198:199], v[152:153]
	v_pk_mul_f32 v[140:141], v[194:195], v[140:141]
	v_pk_fma_f32 v[138:139], v[138:139], s[34:35], v[78:79] op_sel_hi:[1,0,1]
	s_waitcnt lgkmcnt(0)
	v_pk_fma_f32 v[140:141], v[140:141], v[142:143], v[146:147]
	v_pk_fma_f32 v[142:143], v[152:153], v[144:145], v[148:149]
	v_pk_fma_f32 v[144:145], v[140:141], s[34:35], v[74:75] op_sel_hi:[1,0,1]
	v_pk_fma_f32 v[146:147], v[142:143], s[34:35], v[76:77] op_sel_hi:[1,0,1]
	v_pk_mov_b32 v[140:141], v[138:139], v[150:151] op_sel:[1,0]
	v_mov_b32_e32 v142, v138
	v_mov_b32_e32 v143, v151
	v_pk_add_f32 v[140:141], v[140:141], v[142:143]
	v_pk_mul_f32 v[142:143], v[150:151], v[150:151]
	v_pk_mul_f32 v[148:149], v[138:139], v[138:139]
	v_mul_f32_e32 v1, v147, v147
	v_pk_mov_b32 v[152:153], v[148:149], v[142:143] op_sel:[1,0]
	v_mov_b32_e32 v149, v143
	v_pk_add_f32 v[142:143], v[152:153], v[148:149]
	v_pk_add_f32 v[140:141], v[140:141], v[140:141] op_sel:[0,1] op_sel_hi:[1,0]
	v_pk_add_f32 v[142:143], v[142:143], v[142:143] op_sel_hi:[0,1]
	v_mul_f32_e32 v142, v144, v144
	v_pk_fma_f32 v[148:149], v[144:145], v[144:145], v[142:143] op_sel_hi:[1,1,0]
	v_mov_b32_e32 v142, v147
	v_mov_b32_e32 v148, v146
	v_pk_add_f32 v[142:143], v[148:149], v[142:143]
	v_pk_mov_b32 v[148:149], v[144:145], v[146:147] op_sel:[1,0]
	v_mov_b32_e32 v141, v1
	v_pk_add_f32 v[152:153], v[148:149], v[144:145]
	v_pk_mul_f32 v[148:149], v[148:149], v[146:147] op_sel_hi:[1,0]
	s_nop 0
	v_mov_b32_e32 v153, v149
	v_pk_add_f32 v[140:141], v[152:153], v[140:141]
	s_nop 0
	v_pk_add_f32 v[140:141], v[140:141], v[142:143]
	v_cvt_pk_bf16_f32 v142, v138, v139
	v_cvt_pk_bf16_f32 v143, v150, v151
	v_cvt_pk_bf16_f32 v144, v144, v145
	v_cvt_pk_bf16_f32 v145, v146, v147
	global_store_dwordx4 v[158:159], v[142:145], off offset:256
	v_pk_add_f32 v[140:141], v[160:161], v[140:141]
	ds_bpermute_b32 v148, v214, v140
	ds_bpermute_b32 v149, v214, v141
	s_waitcnt lgkmcnt(0)
	v_pk_add_f32 v[138:139], v[140:141], v[148:149]
	ds_bpermute_b32 v140, v215, v138
	ds_bpermute_b32 v141, v215, v139
	s_and_saveexec_b64 s[72:73], s[38:39]
	s_cbranch_execz .LBB0_428
	s_lshl_b32 s7, s58, 3
	s_waitcnt lgkmcnt(0)
	v_pk_add_f32 v[138:139], v[138:139], v[140:141]
	v_lshlrev_b64 v[140:141], 7, v[192:193]
	s_or_b32 s12, s7, s23
	v_lshl_add_u64 v[140:141], s[46:47], 0, v[140:141]
	s_ashr_i32 s13, s12, 31
	v_lshl_add_u64 v[140:141], s[12:13], 2, v[140:141]
	global_store_dwordx2 v[140:141], v[138:139], off
.LBB0_428:
	s_or_b64 exec, exec, s[72:73]
	v_mov_b32_e32 v142, 1.0
	v_mov_b32_e32 v150, 0
	s_and_b64 vcc, exec, s[42:43]
	v_mov_b32_e32 v156, 0
	v_mov_b32_e32 v154, 1.0
	s_cbranch_vccnz .LBB0_430
	ds_read_b64 v[156:157], v213 offset:384
	s_waitcnt lgkmcnt(0)
	v_mov_b32_e32 v154, v157
.LBB0_430:
	s_and_b64 vcc, exec, s[42:43]
	v_mov_b32_e32 v143, 1.0
	v_mov_b32_e32 v144, 1.0
	v_mov_b32_e32 v145, 1.0
	v_mov_b32_e32 v138, 1.0
	v_mov_b32_e32 v139, 1.0
	s_waitcnt lgkmcnt(1)
	v_mov_b32_e32 v140, 1.0
	s_waitcnt lgkmcnt(0)
	v_mov_b32_e32 v141, 1.0
	v_mov_b32_e32 v151, 0
	v_mov_b32_e32 v152, 0
	v_mov_b32_e32 v153, 0
	v_mov_b32_e32 v146, 0
	v_mov_b32_e32 v147, 0
	v_mov_b32_e32 v148, 0
	v_mov_b32_e32 v149, 0
	s_cbranch_vccnz .LBB0_432
	ds_read_b128 v[142:145], v212 offset:2048
	ds_read_b128 v[138:141], v212 offset:2064
	ds_read_b128 v[150:153], v212 offset:3072
	ds_read_b128 v[146:149], v212 offset:3088
.LBB0_432:
	s_waitcnt vmcnt(3)
	v_lshlrev_b32_e32 v1, 16, v134
	v_and_b32_e32 v134, 0xffff0000, v134
	v_lshlrev_b32_e32 v155, 16, v135
	v_and_b32_e32 v157, 0xffff0000, v135
	v_lshlrev_b32_e32 v160, 16, v136
	v_and_b32_e32 v161, 0xffff0000, v136
	v_lshlrev_b32_e32 v192, 16, v137
	v_and_b32_e32 v193, 0xffff0000, v137
	v_sub_f32_e32 v135, v134, v156
	v_sub_f32_e32 v134, v1, v156
	v_sub_f32_e32 v137, v157, v156
	v_sub_f32_e32 v136, v155, v156
	v_pk_mul_f32 v[136:137], v[154:155], v[136:137] op_sel_hi:[0,1]
	v_pk_mul_f32 v[134:135], v[154:155], v[134:135] op_sel_hi:[0,1]
	s_waitcnt lgkmcnt(1)
	v_pk_fma_f32 v[134:135], v[134:135], v[142:143], v[150:151]
	v_pk_fma_f32 v[136:137], v[136:137], v[144:145], v[152:153]
	v_pk_fma_f32 v[158:159], v[134:135], s[34:35], v[86:87] op_sel_hi:[1,0,1]
	v_pk_fma_f32 v[152:153], v[136:137], s[34:35], v[88:89] op_sel_hi:[1,0,1]
	v_sub_f32_e32 v135, v161, v156
	v_sub_f32_e32 v134, v160, v156
	v_sub_f32_e32 v137, v193, v156
	v_sub_f32_e32 v136, v192, v156
	v_pk_mul_f32 v[136:137], v[154:155], v[136:137] op_sel_hi:[0,1]
	v_pk_mul_f32 v[134:135], v[154:155], v[134:135] op_sel_hi:[0,1]
	s_waitcnt lgkmcnt(0)
	v_pk_fma_f32 v[134:135], v[134:135], v[138:139], v[146:147]
	v_pk_fma_f32 v[136:137], v[136:137], v[140:141], v[148:149]
	v_lshl_add_u64 v[138:139], s[8:9], 0, v[190:191]
	v_pk_fma_f32 v[160:161], v[136:137], s[34:35], v[84:85] op_sel_hi:[1,0,1]
	v_pk_fma_f32 v[192:193], v[134:135], s[34:35], v[82:83] op_sel_hi:[1,0,1]
	v_lshl_add_u64 v[150:151], v[182:183], 1, v[138:139]
	s_and_b64 vcc, exec, s[42:43]
	v_cvt_pk_bf16_f32 v134, v158, v159
	v_cvt_pk_bf16_f32 v135, v152, v153
	v_cvt_pk_bf16_f32 v136, v192, v193
	v_cvt_pk_bf16_f32 v137, v160, v161
	global_store_dwordx4 v[150:151], v[134:137], off
	s_cbranch_vccnz .LBB0_434
	ds_read_b128 v[142:145], v212 offset:2560
	ds_read_b128 v[134:137], v212 offset:2576
	ds_read_b128 v[146:149], v212 offset:3584
	ds_read_b128 v[138:141], v212 offset:3600
	s_branch .LBB0_435

.LBB0_435:
	v_mov_b32_e32 v190, v159
	v_mov_b32_e32 v191, v152
	v_mov_b32_e32 v194, v158
	v_mov_b32_e32 v195, v153
	v_pk_add_f32 v[190:191], v[190:191], v[194:195]
	v_mul_f32_e32 v194, v158, v158
	v_pk_fma_f32 v[158:159], v[158:159], v[158:159], v[194:195] op_sel_hi:[1,1,0]
	v_mul_f32_e32 v1, v192, v192
	v_mul_f32_e32 v158, v152, v152
	v_pk_fma_f32 v[152:153], v[152:153], v[152:153], v[158:159] op_sel_hi:[1,1,0]
	v_mov_b32_e32 v158, v160
	v_mov_b32_e32 v152, v161
	v_pk_add_f32 v[152:153], v[158:159], v[152:153]
	v_pk_add_f32 v[158:159], v[192:193], v[192:193] op_sel:[1,0]
	v_pk_mul_f32 v[192:193], v[192:193], v[192:193]
	v_pk_add_f32 v[190:191], v[190:191], v[190:191] op_sel:[0,1] op_sel_hi:[1,0]
	v_mov_b32_e32 v159, v193
	v_mov_b32_e32 v191, v1
	v_pk_add_f32 v[158:159], v[158:159], v[190:191]
	s_waitcnt vmcnt(3)
	v_lshlrev_b32_e32 v157, 16, v131
	v_pk_add_f32 v[152:153], v[158:159], v[152:153]
	v_mul_f32_e32 v158, v160, v160
	v_pk_fma_f32 v[158:159], v[160:161], v[160:161], v[158:159] op_sel_hi:[1,1,0]
	v_lshlrev_b32_e32 v160, 16, v132
	v_mov_b32_e32 v1, v159
	v_and_b32_e32 v158, 0xffff0000, v131
	v_pk_add_f32 v[152:153], v[152:153], v[0:1]
	v_lshlrev_b32_e32 v1, 16, v130
	v_and_b32_e32 v130, 0xffff0000, v130
	v_and_b32_e32 v161, 0xffff0000, v132
	v_lshlrev_b32_e32 v190, 16, v133
	v_and_b32_e32 v191, 0xffff0000, v133
	v_sub_f32_e32 v133, v158, v156
	v_sub_f32_e32 v132, v157, v156
	v_mov_b32_e32 v158, v154
	v_mov_b32_e32 v159, v154
	v_mov_b32_e32 v155, v154
	v_sub_f32_e32 v131, v130, v156
	v_sub_f32_e32 v130, v1, v156
	v_pk_mul_f32 v[132:133], v[158:159], v[132:133]
	v_pk_mul_f32 v[130:131], v[154:155], v[130:131]
	s_waitcnt lgkmcnt(1)
	v_pk_fma_f32 v[132:133], v[132:133], v[144:145], v[148:149]
	v_pk_fma_f32 v[130:131], v[130:131], v[142:143], v[146:147]
	v_pk_fma_f32 v[142:143], v[132:133], s[34:35], v[72:73] op_sel_hi:[1,0,1]
	v_sub_f32_e32 v133, v161, v156
	v_sub_f32_e32 v132, v160, v156
	v_sub_f32_e32 v145, v191, v156
	v_sub_f32_e32 v144, v190, v156
	v_pk_mul_f32 v[144:145], v[158:159], v[144:145]
	v_pk_mul_f32 v[132:133], v[154:155], v[132:133]
	v_pk_fma_f32 v[130:131], v[130:131], s[34:35], v[70:71] op_sel_hi:[1,0,1]
	s_waitcnt lgkmcnt(0)
	v_pk_fma_f32 v[132:133], v[132:133], v[134:135], v[138:139]
	v_pk_fma_f32 v[134:135], v[144:145], v[136:137], v[140:141]
	v_pk_fma_f32 v[136:137], v[132:133], s[34:35], v[66:67] op_sel_hi:[1,0,1]
	v_pk_fma_f32 v[138:139], v[134:135], s[34:35], v[68:69] op_sel_hi:[1,0,1]
	v_pk_mov_b32 v[132:133], v[130:131], v[142:143] op_sel:[1,0]
	v_mov_b32_e32 v134, v130
	v_mov_b32_e32 v135, v143
	v_pk_add_f32 v[132:133], v[132:133], v[134:135]
	v_pk_mul_f32 v[134:135], v[142:143], v[142:143]
	v_pk_mul_f32 v[140:141], v[130:131], v[130:131]
	v_mul_f32_e32 v1, v139, v139
	v_pk_mov_b32 v[144:145], v[140:141], v[134:135] op_sel:[1,0]
	v_mov_b32_e32 v141, v135
	v_pk_add_f32 v[134:135], v[144:145], v[140:141]
	v_pk_add_f32 v[132:133], v[132:133], v[132:133] op_sel:[0,1] op_sel_hi:[1,0]
	v_pk_add_f32 v[134:135], v[134:135], v[134:135] op_sel_hi:[0,1]
	v_mul_f32_e32 v134, v136, v136
	v_pk_fma_f32 v[140:141], v[136:137], v[136:137], v[134:135] op_sel_hi:[1,1,0]
	v_mov_b32_e32 v134, v139
	v_mov_b32_e32 v140, v138
	v_pk_add_f32 v[134:135], v[140:141], v[134:135]
	v_pk_mov_b32 v[140:141], v[136:137], v[138:139] op_sel:[1,0]
	v_mov_b32_e32 v133, v1
	v_pk_add_f32 v[144:145], v[140:141], v[136:137]
	v_pk_mul_f32 v[140:141], v[140:141], v[138:139] op_sel_hi:[1,0]
	s_nop 0
	v_mov_b32_e32 v145, v141
	v_pk_add_f32 v[132:133], v[144:145], v[132:133]
	s_nop 0
	v_pk_add_f32 v[132:133], v[132:133], v[134:135]
	v_cvt_pk_bf16_f32 v134, v130, v131
	v_cvt_pk_bf16_f32 v135, v142, v143
	v_cvt_pk_bf16_f32 v136, v136, v137
	v_cvt_pk_bf16_f32 v137, v138, v139
	global_store_dwordx4 v[150:151], v[134:137], off offset:256
	v_pk_add_f32 v[132:133], v[152:153], v[132:133]
	ds_bpermute_b32 v140, v214, v132
	ds_bpermute_b32 v141, v214, v133
	s_waitcnt lgkmcnt(0)
	v_pk_add_f32 v[130:131], v[132:133], v[140:141]
	ds_bpermute_b32 v132, v215, v130
	ds_bpermute_b32 v133, v215, v131
	s_and_saveexec_b64 s[72:73], s[38:39]
	s_cbranch_execz .LBB0_437
	s_lshl_b32 s7, s58, 3
	s_waitcnt lgkmcnt(0)
	v_pk_add_f32 v[130:131], v[130:131], v[132:133]
	v_lshlrev_b64 v[132:133], 7, v[188:189]
	s_or_b32 s12, s7, s23
	v_lshl_add_u64 v[132:133], s[46:47], 0, v[132:133]
	s_ashr_i32 s13, s12, 31
	v_lshl_add_u64 v[132:133], s[12:13], 2, v[132:133]
	global_store_dwordx2 v[132:133], v[130:131], off
.LBB0_437:
	s_or_b64 exec, exec, s[72:73]
	v_add_u32_e32 v192, 0x80, v184
	v_ashrrev_i32_e32 v193, 31, v192
	v_add_u32_e32 v188, 0x90, v184
	v_lshlrev_b64 v[198:199], 11, v[192:193]
	v_ashrrev_i32_e32 v189, 31, v188
	v_lshl_add_u64 v[130:131], v[186:187], 0, v[198:199]
	v_lshlrev_b64 v[190:191], 11, v[188:189]
	global_load_dwordx4 v[158:161], v[130:131], off
	global_load_dwordx4 v[138:141], v[130:131], off offset:256
	v_lshl_add_u64 v[130:131], v[186:187], 0, v[190:191]
	global_load_dwordx4 v[134:137], v[130:131], off
	s_waitcnt lgkmcnt(0)
	global_load_dwordx4 v[130:133], v[130:131], off offset:256
	v_mov_b32_e32 v146, 1.0
	v_mov_b32_e32 v154, 0
	s_and_b64 vcc, exec, s[42:43]
	v_mov_b32_e32 v196, 0
	v_mov_b32_e32 v194, 1.0
	s_cbranch_vccnz .LBB0_439
	ds_read_b64 v[196:197], v213 offset:1024
	s_waitcnt lgkmcnt(0)
	v_mov_b32_e32 v194, v197

.LBB0_441:
	s_waitcnt vmcnt(3)
	v_lshlrev_b32_e32 v1, 16, v158
	v_and_b32_e32 v158, 0xffff0000, v158
	v_lshlrev_b32_e32 v195, 16, v159
	v_and_b32_e32 v197, 0xffff0000, v159
	v_lshlrev_b32_e32 v202, 16, v160
	v_and_b32_e32 v203, 0xffff0000, v160
	v_lshlrev_b32_e32 v204, 16, v161
	v_and_b32_e32 v205, 0xffff0000, v161
	v_sub_f32_e32 v159, v158, v196
	v_sub_f32_e32 v158, v1, v196
	v_sub_f32_e32 v161, v197, v196
	v_sub_f32_e32 v160, v195, v196
	v_pk_mul_f32 v[160:161], v[194:195], v[160:161] op_sel_hi:[0,1]
	v_pk_mul_f32 v[158:159], v[194:195], v[158:159] op_sel_hi:[0,1]
	s_waitcnt lgkmcnt(1)
	v_pk_fma_f32 v[146:147], v[158:159], v[146:147], v[154:155]
	v_pk_fma_f32 v[148:149], v[160:161], v[148:149], v[156:157]
	v_pk_fma_f32 v[200:201], v[146:147], s[34:35], v[62:63] op_sel_hi:[1,0,1]
	v_pk_fma_f32 v[160:161], v[148:149], s[34:35], v[64:65] op_sel_hi:[1,0,1]
	v_sub_f32_e32 v147, v203, v196
	v_sub_f32_e32 v146, v202, v196
	v_sub_f32_e32 v149, v205, v196
	v_sub_f32_e32 v148, v204, v196
	v_pk_mul_f32 v[148:149], v[194:195], v[148:149] op_sel_hi:[0,1]
	v_pk_mul_f32 v[146:147], v[194:195], v[146:147] op_sel_hi:[0,1]
	s_waitcnt lgkmcnt(0)
	v_pk_fma_f32 v[142:143], v[146:147], v[142:143], v[150:151]
	v_pk_fma_f32 v[144:145], v[148:149], v[144:145], v[152:153]
	v_lshl_add_u64 v[146:147], s[8:9], 0, v[198:199]
	v_pk_fma_f32 v[202:203], v[144:145], s[34:35], v[60:61] op_sel_hi:[1,0,1]
	v_pk_fma_f32 v[204:205], v[142:143], s[34:35], v[58:59] op_sel_hi:[1,0,1]
	v_lshl_add_u64 v[158:159], v[182:183], 1, v[146:147]
	s_and_b64 vcc, exec, s[42:43]
	v_cvt_pk_bf16_f32 v142, v200, v201
	v_cvt_pk_bf16_f32 v143, v160, v161
	v_cvt_pk_bf16_f32 v144, v204, v205
	v_cvt_pk_bf16_f32 v145, v202, v203
	global_store_dwordx4 v[158:159], v[142:145], off
	s_cbranch_vccnz .LBB0_443
	ds_read_b128 v[150:153], v212 offset:2560
	ds_read_b128 v[142:145], v212 offset:2576
	ds_read_b128 v[154:157], v212 offset:3584
	ds_read_b128 v[146:149], v212 offset:3600
	s_branch .LBB0_444

.LBB0_444:
	v_mov_b32_e32 v198, v201
	v_mov_b32_e32 v199, v160
	v_mov_b32_e32 v216, v200
	v_mov_b32_e32 v217, v161
	v_pk_add_f32 v[198:199], v[198:199], v[216:217]
	v_mul_f32_e32 v216, v200, v200
	v_pk_fma_f32 v[200:201], v[200:201], v[200:201], v[216:217] op_sel_hi:[1,1,0]
	v_mul_f32_e32 v1, v204, v204
	v_mul_f32_e32 v200, v160, v160
	v_pk_fma_f32 v[160:161], v[160:161], v[160:161], v[200:201] op_sel_hi:[1,1,0]
	v_mov_b32_e32 v200, v202
	v_mov_b32_e32 v160, v203
	v_pk_add_f32 v[160:161], v[200:201], v[160:161]
	v_pk_add_f32 v[200:201], v[204:205], v[204:205] op_sel:[1,0]
	v_pk_mul_f32 v[204:205], v[204:205], v[204:205]
	v_pk_add_f32 v[198:199], v[198:199], v[198:199] op_sel:[0,1] op_sel_hi:[1,0]
	v_mov_b32_e32 v201, v205
	v_mov_b32_e32 v199, v1
	v_pk_add_f32 v[198:199], v[200:201], v[198:199]
	s_waitcnt vmcnt(3)
	v_lshlrev_b32_e32 v197, 16, v139
	v_pk_add_f32 v[160:161], v[198:199], v[160:161]
	v_mul_f32_e32 v198, v202, v202
	v_pk_fma_f32 v[198:199], v[202:203], v[202:203], v[198:199] op_sel_hi:[1,1,0]
	v_lshlrev_b32_e32 v200, 16, v140
	v_mov_b32_e32 v1, v199
	v_and_b32_e32 v198, 0xffff0000, v139
	v_pk_add_f32 v[160:161], v[160:161], v[0:1]
	v_lshlrev_b32_e32 v1, 16, v138
	v_and_b32_e32 v138, 0xffff0000, v138
	v_and_b32_e32 v201, 0xffff0000, v140
	v_lshlrev_b32_e32 v202, 16, v141
	v_and_b32_e32 v203, 0xffff0000, v141
	v_sub_f32_e32 v141, v198, v196
	v_sub_f32_e32 v140, v197, v196
	v_mov_b32_e32 v198, v194
	v_mov_b32_e32 v199, v194
	v_mov_b32_e32 v195, v194
	v_sub_f32_e32 v139, v138, v196
	v_sub_f32_e32 v138, v1, v196
	v_pk_mul_f32 v[140:141], v[198:199], v[140:141]
	v_pk_mul_f32 v[138:139], v[194:195], v[138:139]
	s_waitcnt lgkmcnt(1)
	v_pk_fma_f32 v[140:141], v[140:141], v[152:153], v[156:157]
	v_pk_fma_f32 v[138:139], v[138:139], v[150:151], v[154:155]
	v_pk_fma_f32 v[150:151], v[140:141], s[34:35], v[48:49] op_sel_hi:[1,0,1]
	v_sub_f32_e32 v141, v201, v196
	v_sub_f32_e32 v140, v200, v196
	v_sub_f32_e32 v153, v203, v196
	v_sub_f32_e32 v152, v202, v196
	v_pk_mul_f32 v[152:153], v[198:199], v[152:153]
	v_pk_mul_f32 v[140:141], v[194:195], v[140:141]
	v_pk_fma_f32 v[138:139], v[138:139], s[34:35], v[46:47] op_sel_hi:[1,0,1]
	s_waitcnt lgkmcnt(0)
	v_pk_fma_f32 v[140:141], v[140:141], v[142:143], v[146:147]
	v_pk_fma_f32 v[142:143], v[152:153], v[144:145], v[148:149]
	v_pk_fma_f32 v[144:145], v[140:141], s[34:35], v[42:43] op_sel_hi:[1,0,1]
	v_pk_fma_f32 v[146:147], v[142:143], s[34:35], v[44:45] op_sel_hi:[1,0,1]
	v_pk_mov_b32 v[140:141], v[138:139], v[150:151] op_sel:[1,0]
	v_mov_b32_e32 v142, v138
	v_mov_b32_e32 v143, v151
	v_pk_add_f32 v[140:141], v[140:141], v[142:143]
	v_pk_mul_f32 v[142:143], v[150:151], v[150:151]
	v_pk_mul_f32 v[148:149], v[138:139], v[138:139]
	v_mul_f32_e32 v1, v147, v147
	v_pk_mov_b32 v[152:153], v[148:149], v[142:143] op_sel:[1,0]
	v_mov_b32_e32 v149, v143
	v_pk_add_f32 v[142:143], v[152:153], v[148:149]
	v_pk_add_f32 v[140:141], v[140:141], v[140:141] op_sel:[0,1] op_sel_hi:[1,0]
	v_pk_add_f32 v[142:143], v[142:143], v[142:143] op_sel_hi:[0,1]
	v_mul_f32_e32 v142, v144, v144
	v_pk_fma_f32 v[148:149], v[144:145], v[144:145], v[142:143] op_sel_hi:[1,1,0]
	v_mov_b32_e32 v142, v147
	v_mov_b32_e32 v148, v146
	v_pk_add_f32 v[142:143], v[148:149], v[142:143]
	v_pk_mov_b32 v[148:149], v[144:145], v[146:147] op_sel:[1,0]
	v_mov_b32_e32 v141, v1
	v_pk_add_f32 v[152:153], v[148:149], v[144:145]
	v_pk_mul_f32 v[148:149], v[148:149], v[146:147] op_sel_hi:[1,0]
	s_nop 0
	v_mov_b32_e32 v153, v149
	v_pk_add_f32 v[140:141], v[152:153], v[140:141]
	s_nop 0
	v_pk_add_f32 v[140:141], v[140:141], v[142:143]
	v_cvt_pk_bf16_f32 v142, v138, v139
	v_cvt_pk_bf16_f32 v143, v150, v151
	v_cvt_pk_bf16_f32 v144, v144, v145
	v_cvt_pk_bf16_f32 v145, v146, v147
	global_store_dwordx4 v[158:159], v[142:145], off offset:256
	v_pk_add_f32 v[140:141], v[160:161], v[140:141]
	ds_bpermute_b32 v148, v214, v140
	ds_bpermute_b32 v149, v214, v141
	s_waitcnt lgkmcnt(0)
	v_pk_add_f32 v[138:139], v[140:141], v[148:149]
	ds_bpermute_b32 v140, v215, v138
	ds_bpermute_b32 v141, v215, v139
	s_and_saveexec_b64 s[72:73], s[38:39]
	s_cbranch_execz .LBB0_446
	s_lshl_b32 s7, s58, 3
	s_waitcnt lgkmcnt(0)
	v_pk_add_f32 v[138:139], v[138:139], v[140:141]
	v_lshlrev_b64 v[140:141], 7, v[192:193]
	s_or_b32 s12, s7, s23
	v_lshl_add_u64 v[140:141], s[46:47], 0, v[140:141]
	s_ashr_i32 s13, s12, 31
	v_lshl_add_u64 v[140:141], s[12:13], 2, v[140:141]
	global_store_dwordx2 v[140:141], v[138:139], off

.LBB0_450:
	s_waitcnt vmcnt(3)
	v_lshlrev_b32_e32 v1, 16, v134
	v_and_b32_e32 v134, 0xffff0000, v134
	v_lshlrev_b32_e32 v155, 16, v135
	v_and_b32_e32 v157, 0xffff0000, v135
	v_lshlrev_b32_e32 v160, 16, v136
	v_and_b32_e32 v161, 0xffff0000, v136
	v_lshlrev_b32_e32 v192, 16, v137
	v_and_b32_e32 v193, 0xffff0000, v137
	v_sub_f32_e32 v135, v134, v156
	v_sub_f32_e32 v134, v1, v156
	v_sub_f32_e32 v137, v157, v156
	v_sub_f32_e32 v136, v155, v156
	v_pk_mul_f32 v[136:137], v[154:155], v[136:137] op_sel_hi:[0,1]
	v_pk_mul_f32 v[134:135], v[154:155], v[134:135] op_sel_hi:[0,1]
	s_waitcnt lgkmcnt(1)
	v_pk_fma_f32 v[134:135], v[134:135], v[142:143], v[150:151]
	v_pk_fma_f32 v[136:137], v[136:137], v[144:145], v[152:153]
	v_pk_fma_f32 v[158:159], v[134:135], s[34:35], v[54:55] op_sel_hi:[1,0,1]
	v_pk_fma_f32 v[152:153], v[136:137], s[34:35], v[56:57] op_sel_hi:[1,0,1]
	v_sub_f32_e32 v135, v161, v156
	v_sub_f32_e32 v134, v160, v156
	v_sub_f32_e32 v137, v193, v156
	v_sub_f32_e32 v136, v192, v156
	v_pk_mul_f32 v[136:137], v[154:155], v[136:137] op_sel_hi:[0,1]
	v_pk_mul_f32 v[134:135], v[154:155], v[134:135] op_sel_hi:[0,1]
	s_waitcnt lgkmcnt(0)
	v_pk_fma_f32 v[134:135], v[134:135], v[138:139], v[146:147]
	v_pk_fma_f32 v[136:137], v[136:137], v[140:141], v[148:149]
	v_lshl_add_u64 v[138:139], s[8:9], 0, v[190:191]
	v_pk_fma_f32 v[160:161], v[136:137], s[34:35], v[52:53] op_sel_hi:[1,0,1]
	v_pk_fma_f32 v[192:193], v[134:135], s[34:35], v[50:51] op_sel_hi:[1,0,1]
	v_lshl_add_u64 v[150:151], v[182:183], 1, v[138:139]
	s_and_b64 vcc, exec, s[42:43]
	v_cvt_pk_bf16_f32 v134, v158, v159
	v_cvt_pk_bf16_f32 v135, v152, v153
	v_cvt_pk_bf16_f32 v136, v192, v193
	v_cvt_pk_bf16_f32 v137, v160, v161
	global_store_dwordx4 v[150:151], v[134:137], off
	s_cbranch_vccnz .LBB0_452
	ds_read_b128 v[142:145], v212 offset:2560
	ds_read_b128 v[134:137], v212 offset:2576
	ds_read_b128 v[146:149], v212 offset:3584
	ds_read_b128 v[138:141], v212 offset:3600
	s_branch .LBB0_453

.LBB0_453:
	v_mov_b32_e32 v190, v159
	v_mov_b32_e32 v191, v152
	v_mov_b32_e32 v194, v158
	v_mov_b32_e32 v195, v153
	v_pk_add_f32 v[190:191], v[190:191], v[194:195]
	v_mul_f32_e32 v194, v158, v158
	v_pk_fma_f32 v[158:159], v[158:159], v[158:159], v[194:195] op_sel_hi:[1,1,0]
	v_mul_f32_e32 v1, v192, v192
	v_mul_f32_e32 v158, v152, v152
	v_pk_fma_f32 v[152:153], v[152:153], v[152:153], v[158:159] op_sel_hi:[1,1,0]
	v_mov_b32_e32 v158, v160
	v_mov_b32_e32 v152, v161
	v_pk_add_f32 v[152:153], v[158:159], v[152:153]
	v_pk_add_f32 v[158:159], v[192:193], v[192:193] op_sel:[1,0]
	v_pk_mul_f32 v[192:193], v[192:193], v[192:193]
	v_pk_add_f32 v[190:191], v[190:191], v[190:191] op_sel:[0,1] op_sel_hi:[1,0]
	v_mov_b32_e32 v159, v193
	v_mov_b32_e32 v191, v1
	v_pk_add_f32 v[158:159], v[158:159], v[190:191]
	s_waitcnt vmcnt(3)
	v_lshlrev_b32_e32 v157, 16, v131
	v_pk_add_f32 v[152:153], v[158:159], v[152:153]
	v_mul_f32_e32 v158, v160, v160
	v_pk_fma_f32 v[158:159], v[160:161], v[160:161], v[158:159] op_sel_hi:[1,1,0]
	v_lshlrev_b32_e32 v160, 16, v132
	v_mov_b32_e32 v1, v159
	v_and_b32_e32 v158, 0xffff0000, v131
	v_pk_add_f32 v[152:153], v[152:153], v[0:1]
	v_lshlrev_b32_e32 v1, 16, v130
	v_and_b32_e32 v130, 0xffff0000, v130
	v_and_b32_e32 v161, 0xffff0000, v132
	v_lshlrev_b32_e32 v190, 16, v133
	v_and_b32_e32 v191, 0xffff0000, v133
	v_sub_f32_e32 v133, v158, v156
	v_sub_f32_e32 v132, v157, v156
	v_mov_b32_e32 v158, v154
	v_mov_b32_e32 v159, v154
	v_mov_b32_e32 v155, v154
	v_sub_f32_e32 v131, v130, v156
	v_sub_f32_e32 v130, v1, v156
	v_pk_mul_f32 v[132:133], v[158:159], v[132:133]
	v_pk_mul_f32 v[130:131], v[154:155], v[130:131]
	s_waitcnt lgkmcnt(1)
	v_pk_fma_f32 v[132:133], v[132:133], v[144:145], v[148:149]
	v_pk_fma_f32 v[130:131], v[130:131], v[142:143], v[146:147]
	v_pk_fma_f32 v[142:143], v[132:133], s[34:35], v[32:33] op_sel_hi:[1,0,1]
	v_sub_f32_e32 v133, v161, v156
	v_sub_f32_e32 v132, v160, v156
	v_sub_f32_e32 v145, v191, v156
	v_sub_f32_e32 v144, v190, v156
	v_pk_mul_f32 v[144:145], v[158:159], v[144:145]
	v_pk_mul_f32 v[132:133], v[154:155], v[132:133]
	v_pk_fma_f32 v[130:131], v[130:131], s[34:35], v[30:31] op_sel_hi:[1,0,1]
	s_waitcnt lgkmcnt(0)
	v_pk_fma_f32 v[132:133], v[132:133], v[134:135], v[138:139]
	v_pk_fma_f32 v[134:135], v[144:145], v[136:137], v[140:141]
	v_pk_fma_f32 v[136:137], v[132:133], s[34:35], v[26:27] op_sel_hi:[1,0,1]
	v_pk_fma_f32 v[138:139], v[134:135], s[34:35], v[28:29] op_sel_hi:[1,0,1]
	v_pk_mov_b32 v[132:133], v[130:131], v[142:143] op_sel:[1,0]
	v_mov_b32_e32 v134, v130
	v_mov_b32_e32 v135, v143
	v_pk_add_f32 v[132:133], v[132:133], v[134:135]
	v_pk_mul_f32 v[134:135], v[142:143], v[142:143]
	v_pk_mul_f32 v[140:141], v[130:131], v[130:131]
	v_mul_f32_e32 v1, v139, v139
	v_pk_mov_b32 v[144:145], v[140:141], v[134:135] op_sel:[1,0]
	v_mov_b32_e32 v141, v135
	v_pk_add_f32 v[134:135], v[144:145], v[140:141]
	v_pk_add_f32 v[132:133], v[132:133], v[132:133] op_sel:[0,1] op_sel_hi:[1,0]
	v_pk_add_f32 v[134:135], v[134:135], v[134:135] op_sel_hi:[0,1]
	v_mul_f32_e32 v134, v136, v136
	v_pk_fma_f32 v[140:141], v[136:137], v[136:137], v[134:135] op_sel_hi:[1,1,0]
	v_mov_b32_e32 v134, v139
	v_mov_b32_e32 v140, v138
	v_pk_add_f32 v[134:135], v[140:141], v[134:135]
	v_pk_mov_b32 v[140:141], v[136:137], v[138:139] op_sel:[1,0]
	v_mov_b32_e32 v133, v1
	v_pk_add_f32 v[144:145], v[140:141], v[136:137]
	v_pk_mul_f32 v[140:141], v[140:141], v[138:139] op_sel_hi:[1,0]
	s_nop 0
	v_mov_b32_e32 v145, v141
	v_pk_add_f32 v[132:133], v[144:145], v[132:133]
	s_nop 0
	v_pk_add_f32 v[132:133], v[132:133], v[134:135]
	v_cvt_pk_bf16_f32 v134, v130, v131
	v_cvt_pk_bf16_f32 v135, v142, v143
	v_cvt_pk_bf16_f32 v136, v136, v137
	v_cvt_pk_bf16_f32 v137, v138, v139
	global_store_dwordx4 v[150:151], v[134:137], off offset:256
	v_pk_add_f32 v[132:133], v[152:153], v[132:133]
	ds_bpermute_b32 v140, v214, v132
	ds_bpermute_b32 v141, v214, v133
	s_waitcnt lgkmcnt(0)
	v_pk_add_f32 v[130:131], v[132:133], v[140:141]
	ds_bpermute_b32 v132, v215, v130
	ds_bpermute_b32 v133, v215, v131
	s_and_saveexec_b64 s[72:73], s[38:39]
	s_cbranch_execz .LBB0_455
	s_lshl_b32 s7, s58, 3
	s_waitcnt lgkmcnt(0)
	v_pk_add_f32 v[130:131], v[130:131], v[132:133]
	v_lshlrev_b64 v[132:133], 7, v[188:189]
	s_or_b32 s12, s7, s23
	v_lshl_add_u64 v[132:133], s[46:47], 0, v[132:133]
	s_ashr_i32 s13, s12, 31
	v_lshl_add_u64 v[132:133], s[12:13], 2, v[132:133]
	global_store_dwordx2 v[132:133], v[130:131], off
.LBB0_455:
	s_or_b64 exec, exec, s[72:73]
	v_add_u32_e32 v192, 0xa0, v184
	v_ashrrev_i32_e32 v193, 31, v192
	v_add_u32_e32 v188, 0xb0, v184
	v_lshlrev_b64 v[196:197], 11, v[192:193]
	v_ashrrev_i32_e32 v189, 31, v188
	v_lshl_add_u64 v[130:131], v[186:187], 0, v[196:197]
	v_lshlrev_b64 v[190:191], 11, v[188:189]
	global_load_dwordx4 v[158:161], v[130:131], off
	global_load_dwordx4 v[138:141], v[130:131], off offset:256
	v_lshl_add_u64 v[130:131], v[186:187], 0, v[190:191]
	global_load_dwordx4 v[134:137], v[130:131], off
	s_waitcnt lgkmcnt(0)
	global_load_dwordx4 v[130:133], v[130:131], off offset:256
	v_mov_b32_e32 v146, 1.0
	v_mov_b32_e32 v154, 0
	s_and_b64 vcc, exec, s[42:43]
	v_mov_b32_e32 v194, 0
	v_mov_b32_e32 v186, 1.0
	s_cbranch_vccnz .LBB0_457
	ds_read_b64 v[194:195], v213 offset:1280
	s_waitcnt lgkmcnt(0)
	v_mov_b32_e32 v186, v195

.LBB0_459:
	s_waitcnt vmcnt(3)
	v_lshlrev_b32_e32 v1, 16, v158
	v_and_b32_e32 v158, 0xffff0000, v158
	v_lshlrev_b32_e32 v187, 16, v159
	v_and_b32_e32 v195, 0xffff0000, v159
	v_lshlrev_b32_e32 v200, 16, v160
	v_and_b32_e32 v201, 0xffff0000, v160
	v_lshlrev_b32_e32 v202, 16, v161
	v_and_b32_e32 v203, 0xffff0000, v161
	v_sub_f32_e32 v159, v158, v194
	v_sub_f32_e32 v158, v1, v194
	v_sub_f32_e32 v161, v195, v194
	v_sub_f32_e32 v160, v187, v194
	v_pk_mul_f32 v[160:161], v[186:187], v[160:161] op_sel_hi:[0,1]
	v_pk_mul_f32 v[158:159], v[186:187], v[158:159] op_sel_hi:[0,1]
	s_waitcnt lgkmcnt(1)
	v_pk_fma_f32 v[146:147], v[158:159], v[146:147], v[154:155]
	v_pk_fma_f32 v[148:149], v[160:161], v[148:149], v[156:157]
	v_pk_fma_f32 v[198:199], v[146:147], s[34:35], v[38:39] op_sel_hi:[1,0,1]
	v_pk_fma_f32 v[160:161], v[148:149], s[34:35], v[40:41] op_sel_hi:[1,0,1]
	v_sub_f32_e32 v147, v201, v194
	v_sub_f32_e32 v146, v200, v194
	v_sub_f32_e32 v149, v203, v194
	v_sub_f32_e32 v148, v202, v194
	v_pk_mul_f32 v[148:149], v[186:187], v[148:149] op_sel_hi:[0,1]
	v_pk_mul_f32 v[146:147], v[186:187], v[146:147] op_sel_hi:[0,1]
	s_waitcnt lgkmcnt(0)
	v_pk_fma_f32 v[142:143], v[146:147], v[142:143], v[150:151]
	v_pk_fma_f32 v[144:145], v[148:149], v[144:145], v[152:153]
	v_lshl_add_u64 v[146:147], s[8:9], 0, v[196:197]
	v_pk_fma_f32 v[200:201], v[144:145], s[34:35], v[36:37] op_sel_hi:[1,0,1]
	v_pk_fma_f32 v[202:203], v[142:143], s[34:35], v[34:35] op_sel_hi:[1,0,1]
	v_lshl_add_u64 v[158:159], v[182:183], 1, v[146:147]
	s_and_b64 vcc, exec, s[42:43]
	v_cvt_pk_bf16_f32 v142, v198, v199
	v_cvt_pk_bf16_f32 v143, v160, v161
	v_cvt_pk_bf16_f32 v144, v202, v203
	v_cvt_pk_bf16_f32 v145, v200, v201
	global_store_dwordx4 v[158:159], v[142:145], off
	s_cbranch_vccnz .LBB0_461
	ds_read_b128 v[150:153], v212 offset:2560
	ds_read_b128 v[142:145], v212 offset:2576
	ds_read_b128 v[154:157], v212 offset:3584
	ds_read_b128 v[146:149], v212 offset:3600
	s_branch .LBB0_462

.LBB0_462:
	v_mov_b32_e32 v196, v199
	v_mov_b32_e32 v197, v160
	v_mov_b32_e32 v204, v198
	v_mov_b32_e32 v205, v161
	v_pk_add_f32 v[196:197], v[196:197], v[204:205]
	v_mul_f32_e32 v204, v198, v198
	v_pk_fma_f32 v[198:199], v[198:199], v[198:199], v[204:205] op_sel_hi:[1,1,0]
	v_mul_f32_e32 v1, v202, v202
	v_mul_f32_e32 v198, v160, v160
	v_pk_fma_f32 v[160:161], v[160:161], v[160:161], v[198:199] op_sel_hi:[1,1,0]
	v_mov_b32_e32 v198, v200
	v_mov_b32_e32 v160, v201
	v_pk_add_f32 v[160:161], v[198:199], v[160:161]
	v_pk_add_f32 v[198:199], v[202:203], v[202:203] op_sel:[1,0]
	v_pk_mul_f32 v[202:203], v[202:203], v[202:203]
	v_pk_add_f32 v[196:197], v[196:197], v[196:197] op_sel:[0,1] op_sel_hi:[1,0]
	v_mov_b32_e32 v199, v203
	v_mov_b32_e32 v197, v1
	v_pk_add_f32 v[196:197], v[198:199], v[196:197]
	s_waitcnt vmcnt(3)
	v_lshlrev_b32_e32 v195, 16, v139
	v_pk_add_f32 v[160:161], v[196:197], v[160:161]
	v_mul_f32_e32 v196, v200, v200
	v_pk_fma_f32 v[196:197], v[200:201], v[200:201], v[196:197] op_sel_hi:[1,1,0]
	v_lshlrev_b32_e32 v198, 16, v140
	v_mov_b32_e32 v1, v197
	v_and_b32_e32 v196, 0xffff0000, v139
	v_pk_add_f32 v[160:161], v[160:161], v[0:1]
	v_lshlrev_b32_e32 v1, 16, v138
	v_and_b32_e32 v138, 0xffff0000, v138
	v_and_b32_e32 v199, 0xffff0000, v140
	v_lshlrev_b32_e32 v200, 16, v141
	v_and_b32_e32 v201, 0xffff0000, v141
	v_sub_f32_e32 v141, v196, v194
	v_sub_f32_e32 v140, v195, v194
	v_mov_b32_e32 v196, v186
	v_mov_b32_e32 v197, v186
	v_mov_b32_e32 v187, v186
	v_sub_f32_e32 v139, v138, v194
	v_sub_f32_e32 v138, v1, v194
	v_pk_mul_f32 v[140:141], v[196:197], v[140:141]
	v_pk_mul_f32 v[138:139], v[186:187], v[138:139]
	s_waitcnt lgkmcnt(1)
	v_pk_fma_f32 v[140:141], v[140:141], v[152:153], v[156:157]
	v_pk_fma_f32 v[138:139], v[138:139], v[150:151], v[154:155]
	v_pk_fma_f32 v[150:151], v[140:141], s[34:35], v[16:17] op_sel_hi:[1,0,1]
	v_sub_f32_e32 v141, v199, v194
	v_sub_f32_e32 v140, v198, v194
	v_sub_f32_e32 v153, v201, v194
	v_sub_f32_e32 v152, v200, v194
	v_pk_mul_f32 v[152:153], v[196:197], v[152:153]
	v_pk_mul_f32 v[140:141], v[186:187], v[140:141]
	v_pk_fma_f32 v[138:139], v[138:139], s[34:35], v[14:15] op_sel_hi:[1,0,1]
	s_waitcnt lgkmcnt(0)
	v_pk_fma_f32 v[140:141], v[140:141], v[142:143], v[146:147]
	v_pk_fma_f32 v[142:143], v[152:153], v[144:145], v[148:149]
	v_pk_fma_f32 v[144:145], v[140:141], s[34:35], v[10:11] op_sel_hi:[1,0,1]
	v_pk_fma_f32 v[146:147], v[142:143], s[34:35], v[12:13] op_sel_hi:[1,0,1]
	v_pk_mov_b32 v[140:141], v[138:139], v[150:151] op_sel:[1,0]
	v_mov_b32_e32 v142, v138
	v_mov_b32_e32 v143, v151
	v_pk_add_f32 v[140:141], v[140:141], v[142:143]
	v_pk_mul_f32 v[142:143], v[150:151], v[150:151]
	v_pk_mul_f32 v[148:149], v[138:139], v[138:139]
	v_mul_f32_e32 v1, v147, v147
	v_pk_mov_b32 v[152:153], v[148:149], v[142:143] op_sel:[1,0]
	v_mov_b32_e32 v149, v143
	v_pk_add_f32 v[142:143], v[152:153], v[148:149]
	v_pk_add_f32 v[140:141], v[140:141], v[140:141] op_sel:[0,1] op_sel_hi:[1,0]
	v_pk_add_f32 v[142:143], v[142:143], v[142:143] op_sel_hi:[0,1]
	v_mul_f32_e32 v142, v144, v144
	v_pk_fma_f32 v[148:149], v[144:145], v[144:145], v[142:143] op_sel_hi:[1,1,0]
	v_mov_b32_e32 v142, v147
	v_mov_b32_e32 v148, v146
	v_pk_add_f32 v[142:143], v[148:149], v[142:143]
	v_pk_mov_b32 v[148:149], v[144:145], v[146:147] op_sel:[1,0]
	v_mov_b32_e32 v141, v1
	v_pk_add_f32 v[152:153], v[148:149], v[144:145]
	v_pk_mul_f32 v[148:149], v[148:149], v[146:147] op_sel_hi:[1,0]
	s_nop 0
	v_mov_b32_e32 v153, v149
	v_pk_add_f32 v[140:141], v[152:153], v[140:141]
	s_nop 0
	v_pk_add_f32 v[140:141], v[140:141], v[142:143]
	v_cvt_pk_bf16_f32 v142, v138, v139
	v_cvt_pk_bf16_f32 v143, v150, v151
	v_cvt_pk_bf16_f32 v144, v144, v145
	v_cvt_pk_bf16_f32 v145, v146, v147
	global_store_dwordx4 v[158:159], v[142:145], off offset:256
	v_pk_add_f32 v[140:141], v[160:161], v[140:141]
	ds_bpermute_b32 v148, v214, v140
	ds_bpermute_b32 v149, v214, v141
	s_waitcnt lgkmcnt(0)
	v_pk_add_f32 v[138:139], v[140:141], v[148:149]
	ds_bpermute_b32 v140, v215, v138
	ds_bpermute_b32 v141, v215, v139
	s_and_saveexec_b64 s[72:73], s[38:39]
	s_cbranch_execz .LBB0_464
	s_lshl_b32 s7, s58, 3
	s_waitcnt lgkmcnt(0)
	v_pk_add_f32 v[138:139], v[138:139], v[140:141]
	v_lshlrev_b64 v[140:141], 7, v[192:193]
	s_or_b32 s12, s7, s23
	v_lshl_add_u64 v[140:141], s[46:47], 0, v[140:141]
	s_ashr_i32 s13, s12, 31
	v_lshl_add_u64 v[140:141], s[12:13], 2, v[140:141]
	global_store_dwordx2 v[140:141], v[138:139], off
.LBB0_464:
	s_or_b64 exec, exec, s[72:73]
	v_mov_b32_e32 v142, 1.0
	v_mov_b32_e32 v150, 0
	s_and_b64 vcc, exec, s[42:43]
	v_mov_b32_e32 v156, 0
	v_mov_b32_e32 v154, 1.0
	s_cbranch_vccnz .LBB0_466
	ds_read_b64 v[156:157], v213 offset:1408
	s_waitcnt lgkmcnt(0)
	v_mov_b32_e32 v154, v157
.LBB0_466:
	s_and_b64 vcc, exec, s[42:43]
	v_mov_b32_e32 v143, 1.0
	v_mov_b32_e32 v144, 1.0
	v_mov_b32_e32 v145, 1.0
	v_mov_b32_e32 v138, 1.0
	v_mov_b32_e32 v139, 1.0
	s_waitcnt lgkmcnt(1)
	v_mov_b32_e32 v140, 1.0
	s_waitcnt lgkmcnt(0)
	v_mov_b32_e32 v141, 1.0
	v_mov_b32_e32 v151, 0
	v_mov_b32_e32 v152, 0
	v_mov_b32_e32 v153, 0
	v_mov_b32_e32 v146, 0
	v_mov_b32_e32 v147, 0
	v_mov_b32_e32 v148, 0
	v_mov_b32_e32 v149, 0
	s_cbranch_vccnz .LBB0_468
	ds_read_b128 v[142:145], v212 offset:2048
	ds_read_b128 v[138:141], v212 offset:2064
	ds_read_b128 v[150:153], v212 offset:3072
	ds_read_b128 v[146:149], v212 offset:3088
.LBB0_468:
	s_waitcnt vmcnt(3)
	v_lshlrev_b32_e32 v1, 16, v134
	v_and_b32_e32 v134, 0xffff0000, v134
	v_lshlrev_b32_e32 v155, 16, v135
	v_and_b32_e32 v157, 0xffff0000, v135
	v_lshlrev_b32_e32 v160, 16, v136
	v_and_b32_e32 v161, 0xffff0000, v136
	v_lshlrev_b32_e32 v186, 16, v137
	v_and_b32_e32 v187, 0xffff0000, v137
	v_sub_f32_e32 v135, v134, v156
	v_sub_f32_e32 v134, v1, v156
	v_sub_f32_e32 v137, v157, v156
	v_sub_f32_e32 v136, v155, v156
	v_pk_mul_f32 v[136:137], v[154:155], v[136:137] op_sel_hi:[0,1]
	v_pk_mul_f32 v[134:135], v[154:155], v[134:135] op_sel_hi:[0,1]
	s_waitcnt lgkmcnt(1)
	v_pk_fma_f32 v[134:135], v[134:135], v[142:143], v[150:151]
	v_pk_fma_f32 v[136:137], v[136:137], v[144:145], v[152:153]
	v_pk_fma_f32 v[158:159], v[134:135], s[34:35], v[22:23] op_sel_hi:[1,0,1]
	v_pk_fma_f32 v[152:153], v[136:137], s[34:35], v[24:25] op_sel_hi:[1,0,1]
	v_sub_f32_e32 v135, v161, v156
	v_sub_f32_e32 v134, v160, v156
	v_sub_f32_e32 v137, v187, v156
	v_sub_f32_e32 v136, v186, v156
	v_pk_mul_f32 v[136:137], v[154:155], v[136:137] op_sel_hi:[0,1]
	v_pk_mul_f32 v[134:135], v[154:155], v[134:135] op_sel_hi:[0,1]
	s_waitcnt lgkmcnt(0)
	v_pk_fma_f32 v[134:135], v[134:135], v[138:139], v[146:147]
	v_pk_fma_f32 v[136:137], v[136:137], v[140:141], v[148:149]
	v_lshl_add_u64 v[138:139], s[8:9], 0, v[190:191]
	v_pk_fma_f32 v[160:161], v[136:137], s[34:35], v[20:21] op_sel_hi:[1,0,1]
	v_pk_fma_f32 v[186:187], v[134:135], s[34:35], v[18:19] op_sel_hi:[1,0,1]
	v_lshl_add_u64 v[150:151], v[182:183], 1, v[138:139]
	s_and_b64 vcc, exec, s[42:43]
	v_cvt_pk_bf16_f32 v134, v158, v159
	v_cvt_pk_bf16_f32 v135, v152, v153
	v_cvt_pk_bf16_f32 v136, v186, v187
	v_cvt_pk_bf16_f32 v137, v160, v161
	global_store_dwordx4 v[150:151], v[134:137], off
	s_cbranch_vccnz .LBB0_470
	ds_read_b128 v[142:145], v212 offset:2560
	ds_read_b128 v[134:137], v212 offset:2576
	ds_read_b128 v[146:149], v212 offset:3584
	ds_read_b128 v[138:141], v212 offset:3600
	s_branch .LBB0_471

.LBB0_471:
	v_mov_b32_e32 v190, v159
	v_mov_b32_e32 v191, v152
	v_mov_b32_e32 v192, v158
	v_mov_b32_e32 v193, v153
	v_pk_add_f32 v[190:191], v[190:191], v[192:193]
	v_mul_f32_e32 v192, v158, v158
	v_pk_fma_f32 v[158:159], v[158:159], v[158:159], v[192:193] op_sel_hi:[1,1,0]
	v_mul_f32_e32 v1, v186, v186
	v_mul_f32_e32 v158, v152, v152
	v_pk_fma_f32 v[152:153], v[152:153], v[152:153], v[158:159] op_sel_hi:[1,1,0]
	v_mov_b32_e32 v158, v160
	v_mov_b32_e32 v152, v161
	v_pk_add_f32 v[152:153], v[158:159], v[152:153]
	v_pk_add_f32 v[158:159], v[186:187], v[186:187] op_sel:[1,0]
	v_pk_mul_f32 v[186:187], v[186:187], v[186:187]
	s_waitcnt vmcnt(3)
	v_lshlrev_b32_e32 v157, 16, v131
	v_mov_b32_e32 v159, v187
	v_pk_add_f32 v[186:187], v[190:191], v[190:191] op_sel:[0,1] op_sel_hi:[1,0]
	v_mov_b32_e32 v155, v154
	v_mov_b32_e32 v187, v1
	v_pk_add_f32 v[158:159], v[158:159], v[186:187]
	v_lshlrev_b32_e32 v186, 16, v133
	v_pk_add_f32 v[152:153], v[158:159], v[152:153]
	v_mul_f32_e32 v158, v160, v160
	v_pk_fma_f32 v[158:159], v[160:161], v[160:161], v[158:159] op_sel_hi:[1,1,0]
	v_lshlrev_b32_e32 v160, 16, v132
	v_mov_b32_e32 v1, v159
	v_and_b32_e32 v158, 0xffff0000, v131
	v_pk_add_f32 v[152:153], v[152:153], v[0:1]
	v_lshlrev_b32_e32 v1, 16, v130
	v_and_b32_e32 v130, 0xffff0000, v130
	v_and_b32_e32 v161, 0xffff0000, v132
	v_and_b32_e32 v187, 0xffff0000, v133
	v_sub_f32_e32 v133, v158, v156
	v_sub_f32_e32 v132, v157, v156
	v_mov_b32_e32 v158, v154
	v_mov_b32_e32 v159, v154
	v_sub_f32_e32 v131, v130, v156
	v_sub_f32_e32 v130, v1, v156
	v_pk_mul_f32 v[132:133], v[158:159], v[132:133]
	v_pk_mul_f32 v[130:131], v[154:155], v[130:131]
	s_waitcnt lgkmcnt(1)
	v_pk_fma_f32 v[132:133], v[132:133], v[144:145], v[148:149]
	v_pk_fma_f32 v[130:131], v[130:131], v[142:143], v[146:147]
	v_pk_fma_f32 v[142:143], v[132:133], s[34:35], v[8:9] op_sel_hi:[1,0,1]
	v_sub_f32_e32 v133, v161, v156
	v_sub_f32_e32 v132, v160, v156
	v_sub_f32_e32 v145, v187, v156
	v_sub_f32_e32 v144, v186, v156
	v_pk_mul_f32 v[144:145], v[158:159], v[144:145]
	v_pk_mul_f32 v[132:133], v[154:155], v[132:133]
	v_pk_fma_f32 v[130:131], v[130:131], s[34:35], v[6:7] op_sel_hi:[1,0,1]
	s_waitcnt lgkmcnt(0)
	v_pk_fma_f32 v[132:133], v[132:133], v[134:135], v[138:139]
	v_pk_fma_f32 v[134:135], v[144:145], v[136:137], v[140:141]
	v_pk_fma_f32 v[136:137], v[132:133], s[34:35], v[2:3] op_sel_hi:[1,0,1]
	v_pk_fma_f32 v[138:139], v[134:135], s[34:35], v[4:5] op_sel_hi:[1,0,1]
	v_pk_mov_b32 v[132:133], v[130:131], v[142:143] op_sel:[1,0]
	v_mov_b32_e32 v134, v130
	v_mov_b32_e32 v135, v143
	v_pk_add_f32 v[132:133], v[132:133], v[134:135]
	v_pk_mul_f32 v[134:135], v[142:143], v[142:143]
	v_pk_mul_f32 v[140:141], v[130:131], v[130:131]
	v_mul_f32_e32 v1, v139, v139
	v_pk_mov_b32 v[144:145], v[140:141], v[134:135] op_sel:[1,0]
	v_mov_b32_e32 v141, v135
	v_pk_add_f32 v[134:135], v[144:145], v[140:141]
	v_pk_add_f32 v[132:133], v[132:133], v[132:133] op_sel:[0,1] op_sel_hi:[1,0]
	v_pk_add_f32 v[134:135], v[134:135], v[134:135] op_sel_hi:[0,1]
	v_mul_f32_e32 v134, v136, v136
	v_pk_fma_f32 v[140:141], v[136:137], v[136:137], v[134:135] op_sel_hi:[1,1,0]
	v_mov_b32_e32 v134, v139
	v_mov_b32_e32 v140, v138
	v_pk_add_f32 v[134:135], v[140:141], v[134:135]
	v_pk_mov_b32 v[140:141], v[136:137], v[138:139] op_sel:[1,0]
	v_mov_b32_e32 v133, v1
	v_pk_add_f32 v[144:145], v[140:141], v[136:137]
	v_pk_mul_f32 v[140:141], v[140:141], v[138:139] op_sel_hi:[1,0]
	s_nop 0
	v_mov_b32_e32 v145, v141
	v_pk_add_f32 v[132:133], v[144:145], v[132:133]
	s_nop 0
	v_pk_add_f32 v[132:133], v[132:133], v[134:135]
	v_cvt_pk_bf16_f32 v134, v130, v131
	v_cvt_pk_bf16_f32 v135, v142, v143
	v_cvt_pk_bf16_f32 v136, v136, v137
	v_cvt_pk_bf16_f32 v137, v138, v139
	global_store_dwordx4 v[150:151], v[134:137], off offset:256
	v_pk_add_f32 v[132:133], v[152:153], v[132:133]
	ds_bpermute_b32 v140, v214, v132
	ds_bpermute_b32 v141, v214, v133
	s_waitcnt lgkmcnt(0)
	v_pk_add_f32 v[130:131], v[132:133], v[140:141]
	ds_bpermute_b32 v132, v215, v130
	ds_bpermute_b32 v133, v215, v131
	s_and_saveexec_b64 s[42:43], s[38:39]
	s_cbranch_execz .LBB0_473
	s_lshl_b32 s7, s58, 3
	s_waitcnt lgkmcnt(0)
	v_pk_add_f32 v[130:131], v[130:131], v[132:133]
	v_lshlrev_b64 v[132:133], 7, v[188:189]
	s_or_b32 s12, s7, s23
	v_lshl_add_u64 v[132:133], s[46:47], 0, v[132:133]
	s_ashr_i32 s13, s12, 31
	v_lshl_add_u64 v[132:133], s[12:13], 2, v[132:133]
	global_store_dwordx2 v[132:133], v[130:131], off

.LBB0_490:
	s_cmp_ge_u32 s23, s22
	s_cbranch_scc1 .LBB0_489
	s_waitcnt vmcnt(0)
	v_lshl_add_u64 v[2:3], v[182:183], 0, v[116:117]
	v_add_co_u32_e32 v2, vcc, 0x9db0000, v2
	ds_bpermute_b32 v88, v131, v123
	s_nop 0
	v_addc_co_u32_e32 v3, vcc, 0, v3, vcc
	global_load_dwordx4 v[12:15], v[2:3], off
	global_load_dwordx4 v[8:11], v[2:3], off offset:64
	global_load_dwordx4 v[60:63], v[140:141], off
	global_load_dwordx4 v[68:71], v[140:141], off offset:64
	global_load_dwordx4 v[48:51], v[140:141], off offset:2048
	global_load_dwordx4 v[52:55], v[140:141], off offset:2112
	global_load_dwordx4 v[44:47], v[142:143], off
	global_load_dwordx4 v[40:43], v[144:145], off
	global_load_dwordx4 v[36:39], v[146:147], off
	global_load_dwordx4 v[32:35], v[148:149], off
	global_load_dwordx4 v[28:31], v[150:151], off
	global_load_dwordx4 v[24:27], v[152:153], off
	global_load_dwordx4 v[56:59], v[154:155], off offset:1024
	global_load_dwordx4 v[64:67], v[154:155], off offset:1088
	s_waitcnt lgkmcnt(1)
	global_load_dwordx4 v[16:19], v[156:157], off offset:1024
	global_load_dwordx4 v[84:87], v[156:157], off offset:1088
	global_load_dwordx4 v[80:83], v[158:159], off offset:1024
	global_load_dwordx4 v[20:23], v[158:159], off offset:1088
	global_load_dwordx4 v[76:79], v[160:161], off offset:1024
	global_load_dwordx4 v[72:75], v[160:161], off offset:1088
	ds_bpermute_b32 v135, v131, v127
	ds_bpermute_b32 v190, v131, v125
	v_add_u32_e32 v133, s23, v111
	s_waitcnt vmcnt(7)
	v_mfma_f32_16x16x32_bf16 v[56:59], v[56:59], v[12:15], 0
	v_cmp_le_u32_e64 s[60:61], v96, v133
	v_cmp_lt_u32_e64 s[62:63], v96, v133
	v_cmp_le_u32_e64 s[58:59], v98, v133
	s_waitcnt vmcnt(6)
	v_mfma_f32_16x16x32_bf16 v[56:59], v[64:67], v[8:11], v[56:59]
	ds_read_b128 v[64:67], v210 offset:18432
	v_cmp_le_u32_e64 s[56:57], v97, v133
	s_cmp_eq_u32 s23, 0
	s_cbranch_scc1 .LBB0_494
	s_waitcnt vmcnt(5)
	v_mfma_f32_16x16x32_bf16 v[16:19], v[16:19], v[12:15], 0
	v_cmp_le_u32_e32 vcc, v100, v133
	s_waitcnt vmcnt(4)
	v_mfma_f32_16x16x32_bf16 v[16:19], v[84:87], v[8:11], v[16:19]
	ds_read_b128 v[84:87], v210 offset:18496
	s_waitcnt lgkmcnt(0)
	v_sub_f32_e32 v1, v84, v88
	v_mul_f32_e32 v1, 0x3fb8aa3b, v1
	v_exp_f32_e32 v2, v1
	v_sub_f32_e32 v1, v85, v88
	v_mul_f32_e32 v1, 0x3fb8aa3b, v1
	v_exp_f32_e32 v3, v1
	v_sub_f32_e32 v1, v86, v88
	v_mul_f32_e32 v1, 0x3fb8aa3b, v1
	v_pk_mul_f32 v[2:3], v[16:17], v[2:3]
	v_exp_f32_e32 v16, v1
	v_sub_f32_e32 v1, v87, v88
	v_mul_f32_e32 v1, 0x3fb8aa3b, v1
	v_exp_f32_e32 v17, v1
	v_cvt_pk_bf16_f32 v1, v2, v3
	v_cndmask_b32_e32 v2, 0, v1, vcc
	v_cmp_le_u32_e32 vcc, v99, v133
	v_pk_mul_f32 v[16:17], v[18:19], v[16:17]
	s_nop 0
	v_cndmask_b32_sdwa v1, v0, v1, vcc dst_sel:DWORD dst_unused:UNUSED_PAD src0_sel:DWORD src1_sel:WORD_1
	v_perm_b32 v18, v1, v2, s85
	v_cvt_pk_bf16_f32 v1, v16, v17
	v_cmp_le_u32_e32 vcc, v102, v133
	s_nop 1
	v_cndmask_b32_e32 v2, 0, v1, vcc
	v_cmp_le_u32_e32 vcc, v101, v133
	s_nop 1
	v_cndmask_b32_sdwa v1, v0, v1, vcc dst_sel:DWORD dst_unused:UNUSED_PAD src0_sel:DWORD src1_sel:WORD_1
	v_perm_b32 v19, v1, v2, s85
	s_cmp_lt_u32 s69, 2
	s_cbranch_scc1 .LBB0_495
